# stack-all GEMM loops with a rolling vmcnt(8) in front of every leading barrier (each LDS-DMA load gets two segments to land) instead of vmcnt(6) at segments 2 and 4
# baseline (speedup 1.0000x reference)
.LBB0_37:
	s_add_i32 s69, s48, 2
	s_add_u32 s46, s0, 0x100
	s_addc_u32 s47, s1, 0
	s_add_i32 s70, 0, 0x10000
	ds_read_b128 v[140:143], v153
	ds_read_b128 v[144:147], v153 offset:1024
	ds_read_b128 v[148:151], v153 offset:2048
	ds_read_b128 v[168:171], v153 offset:3072
	s_cmp_eq_u32 s12, s48
	s_cselect_b32 s48, s44, s13
	s_cselect_b32 s51, s43, s47
	s_cselect_b32 s50, s42, s46
	s_cselect_b32 s49, s45, s68
	ds_read_b128 v[172:175], v155
	ds_read_b128 v[176:179], v155 offset:1024
	ds_read_b128 v[180:183], v155 offset:2048
	ds_read_b128 v[184:187], v155 offset:3072
	ds_read_b128 v[188:191], v155 offset:4096
	ds_read_b128 v[192:195], v155 offset:5120
	ds_read_b128 v[196:199], v155 offset:6144
	ds_read_b128 v[224:227], v155 offset:7168
	s_add_i32 m0, s53, 0xc000
	s_nop 0
	global_load_lds_dwordx4 v136, s[0:1]
	s_add_i32 m0, s53, 0xe000
	s_add_i32 s71, 0, 0x14000
	global_load_lds_dwordx4 v138, s[0:1]
	s_add_i32 s0, s70, s52
	ds_read_b128 v[228:231], v153 offset:16384
	ds_read_b128 v[232:235], v153 offset:17408
	ds_read_b128 v[236:239], v153 offset:18432
	ds_read_b128 v[240:243], v153 offset:19456
	s_waitcnt vmcnt(8) lgkmcnt(0)
	s_barrier
	v_mfma_f32_16x16x32_bf16 v[126:129], v[140:143], v[172:175], v[126:129]
	v_mfma_f32_16x16x32_bf16 v[122:125], v[148:151], v[172:175], v[122:125]
	v_mfma_f32_16x16x32_bf16 v[110:113], v[140:143], v[180:183], v[110:113]
	v_mfma_f32_16x16x32_bf16 v[106:109], v[148:151], v[180:183], v[106:109]
	v_mfma_f32_16x16x32_bf16 v[94:97], v[140:143], v[188:191], v[94:97]
	v_mfma_f32_16x16x32_bf16 v[90:93], v[148:151], v[188:191], v[90:93]
	v_mfma_f32_16x16x32_bf16 v[78:81], v[140:143], v[196:199], v[78:81]
	v_mfma_f32_16x16x32_bf16 v[74:77], v[148:151], v[196:199], v[74:77]
	v_mfma_f32_16x16x32_bf16 v[126:129], v[144:147], v[176:179], v[126:129]
	v_mfma_f32_16x16x32_bf16 v[122:125], v[168:171], v[176:179], v[122:125]
	v_mfma_f32_16x16x32_bf16 v[110:113], v[144:147], v[184:187], v[110:113]
	v_mfma_f32_16x16x32_bf16 v[106:109], v[168:171], v[184:187], v[106:109]
	v_mfma_f32_16x16x32_bf16 v[94:97], v[144:147], v[192:195], v[94:97]
	v_mfma_f32_16x16x32_bf16 v[90:93], v[168:171], v[192:195], v[90:93]
	v_mfma_f32_16x16x32_bf16 v[78:81], v[144:147], v[224:227], v[78:81]
	v_mfma_f32_16x16x32_bf16 v[74:77], v[168:171], v[224:227], v[74:77]
	v_mfma_f32_16x16x32_bf16 v[118:121], v[228:231], v[172:175], v[118:121]
	v_mfma_f32_16x16x32_bf16 v[114:117], v[236:239], v[172:175], v[114:117]
	v_mfma_f32_16x16x32_bf16 v[102:105], v[228:231], v[180:183], v[102:105]
	v_mfma_f32_16x16x32_bf16 v[98:101], v[236:239], v[180:183], v[98:101]
	v_mfma_f32_16x16x32_bf16 v[86:89], v[228:231], v[188:191], v[86:89]
	v_mfma_f32_16x16x32_bf16 v[82:85], v[236:239], v[188:191], v[82:85]
	v_mfma_f32_16x16x32_bf16 v[70:73], v[228:231], v[196:199], v[70:73]
	v_mfma_f32_16x16x32_bf16 v[66:69], v[236:239], v[196:199], v[66:69]
	v_mfma_f32_16x16x32_bf16 v[118:121], v[232:235], v[176:179], v[118:121]
	v_mfma_f32_16x16x32_bf16 v[114:117], v[240:243], v[176:179], v[114:117]
	v_mfma_f32_16x16x32_bf16 v[102:105], v[232:235], v[184:187], v[102:105]
	v_mfma_f32_16x16x32_bf16 v[98:101], v[240:243], v[184:187], v[98:101]
	v_mfma_f32_16x16x32_bf16 v[86:89], v[232:235], v[192:195], v[86:89]
	v_mfma_f32_16x16x32_bf16 v[82:85], v[240:243], v[192:195], v[82:85]
	v_mfma_f32_16x16x32_bf16 v[70:73], v[232:235], v[224:227], v[70:73]
	v_mfma_f32_16x16x32_bf16 v[66:69], v[240:243], v[224:227], v[66:69]
	s_barrier
	s_mov_b32 m0, s53
	s_add_u32 s78, s50, s94
	s_addc_u32 s79, s51, s95
	ds_read_b128 v[172:175], v155 offset:16384
	ds_read_b128 v[176:179], v155 offset:17408
	ds_read_b128 v[180:183], v155 offset:18432
	ds_read_b128 v[184:187], v155 offset:19456
	ds_read_b128 v[188:191], v155 offset:20480
	ds_read_b128 v[192:195], v155 offset:21504
	ds_read_b128 v[196:199], v155 offset:22528
	ds_read_b128 v[224:227], v155 offset:23552
	global_load_lds_dwordx4 v134, s[50:51]
	s_mov_b32 m0, s54
	s_add_u32 s76, s48, s94
	s_addc_u32 s77, s49, s95
	global_load_lds_dwordx4 v132, s[50:51]
	s_mov_b32 m0, s0
	s_nop 0
	global_load_lds_dwordx4 v0, s[48:49]
	s_add_i32 m0, s0, 0x2000
	s_add_u32 s0, s48, 0x160000
	s_addc_u32 s1, s49, 0
	global_load_lds_dwordx4 v130, s[48:49]
	s_add_i32 s70, s71, s52
	s_mov_b32 m0, s70
	s_nop 0
	global_load_lds_dwordx4 v0, s[0:1]
	s_add_i32 m0, s70, 0x2000
	s_nop 0
	global_load_lds_dwordx4 v130, s[0:1]
	s_waitcnt vmcnt(8) lgkmcnt(0)
	s_barrier
	v_mfma_f32_16x16x32_bf16 v[62:65], v[140:143], v[172:175], v[62:65]
	v_mfma_f32_16x16x32_bf16 v[58:61], v[148:151], v[172:175], v[58:61]
	v_mfma_f32_16x16x32_bf16 v[46:49], v[140:143], v[180:183], v[46:49]
	v_mfma_f32_16x16x32_bf16 v[42:45], v[148:151], v[180:183], v[42:45]
	v_mfma_f32_16x16x32_bf16 v[30:33], v[140:143], v[188:191], v[30:33]
	v_mfma_f32_16x16x32_bf16 v[26:29], v[148:151], v[188:191], v[26:29]
	v_mfma_f32_16x16x32_bf16 v[14:17], v[140:143], v[196:199], v[14:17]
	v_mfma_f32_16x16x32_bf16 v[10:13], v[148:151], v[196:199], v[10:13]
	v_mfma_f32_16x16x32_bf16 v[62:65], v[144:147], v[176:179], v[62:65]
	v_mfma_f32_16x16x32_bf16 v[58:61], v[168:171], v[176:179], v[58:61]
	v_mfma_f32_16x16x32_bf16 v[46:49], v[144:147], v[184:187], v[46:49]
	v_mfma_f32_16x16x32_bf16 v[42:45], v[168:171], v[184:187], v[42:45]
	v_mfma_f32_16x16x32_bf16 v[30:33], v[144:147], v[192:195], v[30:33]
	v_mfma_f32_16x16x32_bf16 v[26:29], v[168:171], v[192:195], v[26:29]
	v_mfma_f32_16x16x32_bf16 v[14:17], v[144:147], v[224:227], v[14:17]
	v_mfma_f32_16x16x32_bf16 v[10:13], v[168:171], v[224:227], v[10:13]
	v_mfma_f32_16x16x32_bf16 v[54:57], v[228:231], v[172:175], v[54:57]
	v_mfma_f32_16x16x32_bf16 v[50:53], v[236:239], v[172:175], v[50:53]
	v_mfma_f32_16x16x32_bf16 v[38:41], v[228:231], v[180:183], v[38:41]
	v_mfma_f32_16x16x32_bf16 v[34:37], v[236:239], v[180:183], v[34:37]
	v_mfma_f32_16x16x32_bf16 v[22:25], v[228:231], v[188:191], v[22:25]
	v_mfma_f32_16x16x32_bf16 v[18:21], v[236:239], v[188:191], v[18:21]
	v_mfma_f32_16x16x32_bf16 v[6:9], v[228:231], v[196:199], v[6:9]
	v_mfma_f32_16x16x32_bf16 v[2:5], v[236:239], v[196:199], v[2:5]
	v_mfma_f32_16x16x32_bf16 v[54:57], v[232:235], v[176:179], v[54:57]
	v_mfma_f32_16x16x32_bf16 v[50:53], v[240:243], v[176:179], v[50:53]
	v_mfma_f32_16x16x32_bf16 v[38:41], v[232:235], v[184:187], v[38:41]
	v_mfma_f32_16x16x32_bf16 v[34:37], v[240:243], v[184:187], v[34:37]
	v_mfma_f32_16x16x32_bf16 v[22:25], v[232:235], v[192:195], v[22:25]
	v_mfma_f32_16x16x32_bf16 v[18:21], v[240:243], v[192:195], v[18:21]
	v_mfma_f32_16x16x32_bf16 v[6:9], v[232:235], v[224:227], v[6:9]
	v_mfma_f32_16x16x32_bf16 v[2:5], v[240:243], v[224:227], v[2:5]
	s_barrier
	s_add_i32 s70, 0, 0x18000
	ds_read_b128 v[140:143], v153 offset:32768
	ds_read_b128 v[144:147], v153 offset:33792
	ds_read_b128 v[148:151], v153 offset:34816
	ds_read_b128 v[168:171], v153 offset:35840
	s_add_u32 s0, s50, 0x2c0000
	s_addc_u32 s1, s51, 0
	ds_read_b128 v[172:175], v155 offset:32768
	ds_read_b128 v[176:179], v155 offset:33792
	ds_read_b128 v[180:183], v155 offset:34816
	ds_read_b128 v[184:187], v155 offset:35840
	ds_read_b128 v[188:191], v155 offset:36864
	ds_read_b128 v[192:195], v155 offset:37888
	ds_read_b128 v[196:199], v155 offset:38912
	ds_read_b128 v[224:227], v155 offset:39936
	s_mov_b32 m0, s55
	s_nop 0
	global_load_lds_dwordx4 v134, s[0:1]
	s_mov_b32 m0, s56
	s_add_i32 s50, 0, 0x1c000
	global_load_lds_dwordx4 v132, s[0:1]
	s_add_i32 s0, s70, s52
	ds_read_b128 v[228:231], v153 offset:49152
	ds_read_b128 v[232:235], v153 offset:50176
	ds_read_b128 v[236:239], v153 offset:51200
	ds_read_b128 v[240:243], v153 offset:52224
	s_waitcnt vmcnt(8) lgkmcnt(0)
	s_barrier
	v_mfma_f32_16x16x32_bf16 v[126:129], v[140:143], v[172:175], v[126:129]
	v_mfma_f32_16x16x32_bf16 v[122:125], v[148:151], v[172:175], v[122:125]
	v_mfma_f32_16x16x32_bf16 v[110:113], v[140:143], v[180:183], v[110:113]
	v_mfma_f32_16x16x32_bf16 v[106:109], v[148:151], v[180:183], v[106:109]
	v_mfma_f32_16x16x32_bf16 v[94:97], v[140:143], v[188:191], v[94:97]
	v_mfma_f32_16x16x32_bf16 v[90:93], v[148:151], v[188:191], v[90:93]
	v_mfma_f32_16x16x32_bf16 v[78:81], v[140:143], v[196:199], v[78:81]
	v_mfma_f32_16x16x32_bf16 v[74:77], v[148:151], v[196:199], v[74:77]
	v_mfma_f32_16x16x32_bf16 v[126:129], v[144:147], v[176:179], v[126:129]
	v_mfma_f32_16x16x32_bf16 v[122:125], v[168:171], v[176:179], v[122:125]
	v_mfma_f32_16x16x32_bf16 v[110:113], v[144:147], v[184:187], v[110:113]
	v_mfma_f32_16x16x32_bf16 v[106:109], v[168:171], v[184:187], v[106:109]
	v_mfma_f32_16x16x32_bf16 v[94:97], v[144:147], v[192:195], v[94:97]
	v_mfma_f32_16x16x32_bf16 v[90:93], v[168:171], v[192:195], v[90:93]
	v_mfma_f32_16x16x32_bf16 v[78:81], v[144:147], v[224:227], v[78:81]
	v_mfma_f32_16x16x32_bf16 v[74:77], v[168:171], v[224:227], v[74:77]
	v_mfma_f32_16x16x32_bf16 v[118:121], v[228:231], v[172:175], v[118:121]
	v_mfma_f32_16x16x32_bf16 v[114:117], v[236:239], v[172:175], v[114:117]
	v_mfma_f32_16x16x32_bf16 v[102:105], v[228:231], v[180:183], v[102:105]
	v_mfma_f32_16x16x32_bf16 v[98:101], v[236:239], v[180:183], v[98:101]
	v_mfma_f32_16x16x32_bf16 v[86:89], v[228:231], v[188:191], v[86:89]
	v_mfma_f32_16x16x32_bf16 v[82:85], v[236:239], v[188:191], v[82:85]
	v_mfma_f32_16x16x32_bf16 v[70:73], v[228:231], v[196:199], v[70:73]
	v_mfma_f32_16x16x32_bf16 v[66:69], v[236:239], v[196:199], v[66:69]
	v_mfma_f32_16x16x32_bf16 v[118:121], v[232:235], v[176:179], v[118:121]
	v_mfma_f32_16x16x32_bf16 v[114:117], v[240:243], v[176:179], v[114:117]
	v_mfma_f32_16x16x32_bf16 v[102:105], v[232:235], v[184:187], v[102:105]
	v_mfma_f32_16x16x32_bf16 v[98:101], v[240:243], v[184:187], v[98:101]
	v_mfma_f32_16x16x32_bf16 v[86:89], v[232:235], v[192:195], v[86:89]
	v_mfma_f32_16x16x32_bf16 v[82:85], v[240:243], v[192:195], v[82:85]
	v_mfma_f32_16x16x32_bf16 v[70:73], v[232:235], v[224:227], v[70:73]
	v_mfma_f32_16x16x32_bf16 v[66:69], v[240:243], v[224:227], v[66:69]
	s_barrier
	s_mov_b32 m0, s57
	ds_read_b128 v[172:175], v155 offset:49152
	ds_read_b128 v[176:179], v155 offset:50176
	ds_read_b128 v[180:183], v155 offset:51200
	ds_read_b128 v[184:187], v155 offset:52224
	ds_read_b128 v[188:191], v155 offset:53248
	ds_read_b128 v[192:195], v155 offset:54272
	ds_read_b128 v[196:199], v155 offset:55296
	ds_read_b128 v[224:227], v155 offset:56320
	global_load_lds_dwordx4 v134, s[78:79]
	s_mov_b32 m0, s58
	s_nop 0
	global_load_lds_dwordx4 v132, s[78:79]
	s_mov_b32 m0, s0
	s_nop 0
	global_load_lds_dwordx4 v0, s[76:77]
	s_add_i32 m0, s0, 0x2000
	s_add_u32 s0, s48, 0x160080
	s_addc_u32 s1, s49, 0
	global_load_lds_dwordx4 v130, s[76:77]
	s_add_i32 s48, s50, s52
	s_mov_b32 m0, s48
	s_nop 0
	global_load_lds_dwordx4 v0, s[0:1]
	s_add_i32 m0, s48, 0x2000
	s_nop 0
	global_load_lds_dwordx4 v130, s[0:1]
	s_waitcnt vmcnt(8) lgkmcnt(0)
	s_nop 0
	s_barrier
	v_mfma_f32_16x16x32_bf16 v[62:65], v[140:143], v[172:175], v[62:65]
	v_mfma_f32_16x16x32_bf16 v[58:61], v[148:151], v[172:175], v[58:61]
	v_mfma_f32_16x16x32_bf16 v[46:49], v[140:143], v[180:183], v[46:49]
	v_mfma_f32_16x16x32_bf16 v[42:45], v[148:151], v[180:183], v[42:45]
	v_mfma_f32_16x16x32_bf16 v[30:33], v[140:143], v[188:191], v[30:33]
	v_mfma_f32_16x16x32_bf16 v[26:29], v[148:151], v[188:191], v[26:29]
	v_mfma_f32_16x16x32_bf16 v[14:17], v[140:143], v[196:199], v[14:17]
	v_mfma_f32_16x16x32_bf16 v[10:13], v[148:151], v[196:199], v[10:13]
	v_mfma_f32_16x16x32_bf16 v[62:65], v[144:147], v[176:179], v[62:65]
	v_mfma_f32_16x16x32_bf16 v[58:61], v[168:171], v[176:179], v[58:61]
	v_mfma_f32_16x16x32_bf16 v[46:49], v[144:147], v[184:187], v[46:49]
	v_mfma_f32_16x16x32_bf16 v[42:45], v[168:171], v[184:187], v[42:45]
	v_mfma_f32_16x16x32_bf16 v[30:33], v[144:147], v[192:195], v[30:33]
	v_mfma_f32_16x16x32_bf16 v[26:29], v[168:171], v[192:195], v[26:29]
	v_mfma_f32_16x16x32_bf16 v[14:17], v[144:147], v[224:227], v[14:17]
	v_mfma_f32_16x16x32_bf16 v[10:13], v[168:171], v[224:227], v[10:13]
	v_mfma_f32_16x16x32_bf16 v[54:57], v[228:231], v[172:175], v[54:57]
	v_mfma_f32_16x16x32_bf16 v[50:53], v[236:239], v[172:175], v[50:53]
	v_mfma_f32_16x16x32_bf16 v[38:41], v[228:231], v[180:183], v[38:41]
	v_mfma_f32_16x16x32_bf16 v[34:37], v[236:239], v[180:183], v[34:37]
	v_mfma_f32_16x16x32_bf16 v[22:25], v[228:231], v[188:191], v[22:25]
	v_mfma_f32_16x16x32_bf16 v[18:21], v[236:239], v[188:191], v[18:21]
	v_mfma_f32_16x16x32_bf16 v[6:9], v[228:231], v[196:199], v[6:9]
	v_mfma_f32_16x16x32_bf16 v[2:5], v[236:239], v[196:199], v[2:5]
	v_mfma_f32_16x16x32_bf16 v[54:57], v[232:235], v[176:179], v[54:57]
	v_mfma_f32_16x16x32_bf16 v[50:53], v[240:243], v[176:179], v[50:53]
	v_mfma_f32_16x16x32_bf16 v[38:41], v[232:235], v[184:187], v[38:41]
	v_mfma_f32_16x16x32_bf16 v[34:37], v[240:243], v[184:187], v[34:37]
	v_mfma_f32_16x16x32_bf16 v[22:25], v[232:235], v[192:195], v[22:25]
	v_mfma_f32_16x16x32_bf16 v[18:21], v[240:243], v[192:195], v[18:21]
	v_mfma_f32_16x16x32_bf16 v[6:9], v[232:235], v[224:227], v[6:9]
	v_mfma_f32_16x16x32_bf16 v[2:5], v[240:243], v[224:227], v[2:5]
	s_barrier
	s_add_u32 s13, s13, 0x100
	s_addc_u32 s68, s68, 0
	s_mov_b64 s[0:1], s[46:47]
	s_mov_b32 s48, s69
	s_cmp_ge_i32 s69, s39
	s_cbranch_scc0 .LBB0_37
	s_cmp_eq_u32 s65, 2
	s_cbranch_scc1 .Lepi10_orig
	v_readlane_b32 s90, v255, 17
	v_readlane_b32 s91, v255, 18
	v_readlane_b32 s96, v255, 19
	v_readlane_b32 s97, v255, 20
	v_lshl_or_b32 v156, s66, 8, v154
	v_lshlrev_b32_e32 v156, 2, v156
	v_lshl_add_u32 v157, v152, 13, v156
	s_lshl_b32 s72, s67, 21
	s_add_u32 s74, s22, s72
	s_addc_u32 s75, s23, 0
	s_add_u32 s76, s22, s72
	s_addc_u32 s77, s23, 0
	s_lshr_b32 s73, s67, 3
	s_mul_i32 s73, s73, 0xc000
	s_add_u32 s73, s73, 0xa000
	s_add_u32 s70, s90, s73
	s_addc_u32 s71, s91, 0
	global_load_dwordx4 v[140:143], v156, s[70:71]
	global_load_dwordx4 v[144:147], v156, s[70:71] offset:64
	global_load_dwordx4 v[148:151], v156, s[70:71] offset:512
	global_load_dwordx4 v[168:171], v156, s[70:71] offset:576
	global_load_dwordx4 v[224:227], v157, s[74:75] nt
	global_load_dwordx4 v[228:231], v157, s[74:75] offset:64 nt
	global_load_dwordx4 v[232:235], v157, s[74:75] offset:512 nt
	global_load_dwordx4 v[236:239], v157, s[74:75] offset:576 nt
	s_add_u32 s74, s74, 0x20000
	s_addc_u32 s75, s75, 0
	global_load_dwordx4 v[240:243], v157, s[74:75] nt
	global_load_dwordx4 v[244:247], v157, s[74:75] offset:64 nt
	s_waitcnt vmcnt(5)
	v_pk_fma_f32 v[128:129], v[128:129], v[142:143], v[226:227]
	v_pk_fma_f32 v[126:127], v[126:127], v[140:141], v[224:225]
	global_store_dwordx4 v157, v[126:129], s[76:77] nt
	global_load_dwordx4 v[224:227], v157, s[74:75] offset:512 nt
	s_waitcnt vmcnt(6)
	v_pk_fma_f32 v[124:125], v[124:125], v[146:147], v[230:231]
	v_pk_fma_f32 v[122:123], v[122:123], v[144:145], v[228:229]
	global_store_dwordx4 v157, v[122:125], s[76:77] offset:64 nt
	global_load_dwordx4 v[228:231], v157, s[74:75] offset:576 nt
	s_waitcnt vmcnt(7)
	v_pk_fma_f32 v[120:121], v[120:121], v[150:151], v[234:235]
	v_pk_fma_f32 v[118:119], v[118:119], v[148:149], v[232:233]
	global_store_dwordx4 v157, v[118:121], s[76:77] offset:512 nt
	s_add_u32 s74, s74, 0x20000
	s_addc_u32 s75, s75, 0
	global_load_dwordx4 v[232:235], v157, s[74:75] nt
	s_waitcnt vmcnt(8)
	v_pk_fma_f32 v[116:117], v[116:117], v[170:171], v[238:239]
	v_pk_fma_f32 v[114:115], v[114:115], v[168:169], v[236:237]
	global_store_dwordx4 v157, v[114:117], s[76:77] offset:576 nt
	global_load_dwordx4 v[236:239], v157, s[74:75] offset:64 nt
	s_add_u32 s76, s76, 0x20000
	s_addc_u32 s77, s77, 0
	s_waitcnt vmcnt(9)
	v_pk_fma_f32 v[112:113], v[112:113], v[142:143], v[242:243]
	v_pk_fma_f32 v[110:111], v[110:111], v[140:141], v[240:241]
	global_store_dwordx4 v157, v[110:113], s[76:77] nt
	global_load_dwordx4 v[240:243], v157, s[74:75] offset:512 nt
	s_waitcnt vmcnt(10)
	v_pk_fma_f32 v[108:109], v[108:109], v[146:147], v[246:247]
	v_pk_fma_f32 v[106:107], v[106:107], v[144:145], v[244:245]
	global_store_dwordx4 v157, v[106:109], s[76:77] offset:64 nt
	global_load_dwordx4 v[244:247], v157, s[74:75] offset:576 nt
	s_waitcnt vmcnt(10)
	v_pk_fma_f32 v[104:105], v[104:105], v[150:151], v[226:227]
	v_pk_fma_f32 v[102:103], v[102:103], v[148:149], v[224:225]
	global_store_dwordx4 v157, v[102:105], s[76:77] offset:512 nt
	s_add_u32 s74, s74, 0x20000
	s_addc_u32 s75, s75, 0
	global_load_dwordx4 v[224:227], v157, s[74:75] nt
	s_waitcnt vmcnt(10)
	v_pk_fma_f32 v[100:101], v[100:101], v[170:171], v[230:231]
	v_pk_fma_f32 v[98:99], v[98:99], v[168:169], v[228:229]
	global_store_dwordx4 v157, v[98:101], s[76:77] offset:576 nt
	global_load_dwordx4 v[228:231], v157, s[74:75] offset:64 nt
	s_add_u32 s76, s76, 0x20000
	s_addc_u32 s77, s77, 0
	s_waitcnt vmcnt(10)
	v_pk_fma_f32 v[96:97], v[96:97], v[142:143], v[234:235]
	v_pk_fma_f32 v[94:95], v[94:95], v[140:141], v[232:233]
	global_store_dwordx4 v157, v[94:97], s[76:77] nt
	global_load_dwordx4 v[232:235], v157, s[74:75] offset:512 nt
	s_waitcnt vmcnt(10)
	v_pk_fma_f32 v[92:93], v[92:93], v[146:147], v[238:239]
	v_pk_fma_f32 v[90:91], v[90:91], v[144:145], v[236:237]
	global_store_dwordx4 v157, v[90:93], s[76:77] offset:64 nt
	global_load_dwordx4 v[236:239], v157, s[74:75] offset:576 nt
	s_waitcnt vmcnt(10)
	v_pk_fma_f32 v[88:89], v[88:89], v[150:151], v[242:243]
	v_pk_fma_f32 v[86:87], v[86:87], v[148:149], v[240:241]
	global_store_dwordx4 v157, v[86:89], s[76:77] offset:512 nt
	s_add_u32 s74, s74, 0xa0000
	s_addc_u32 s75, s75, 0
	global_load_dwordx4 v[240:243], v157, s[74:75] nt
	s_waitcnt vmcnt(10)
	v_pk_fma_f32 v[84:85], v[84:85], v[170:171], v[246:247]
	v_pk_fma_f32 v[82:83], v[82:83], v[168:169], v[244:245]
	global_store_dwordx4 v157, v[82:85], s[76:77] offset:576 nt
	global_load_dwordx4 v[244:247], v157, s[74:75] offset:64 nt
	s_add_u32 s76, s76, 0x20000
	s_addc_u32 s77, s77, 0
	s_waitcnt vmcnt(10)
	v_pk_fma_f32 v[80:81], v[80:81], v[142:143], v[226:227]
	v_pk_fma_f32 v[78:79], v[78:79], v[140:141], v[224:225]
	global_store_dwordx4 v157, v[78:81], s[76:77] nt
	global_load_dwordx4 v[224:227], v157, s[74:75] offset:512 nt
	s_waitcnt vmcnt(10)
	v_pk_fma_f32 v[76:77], v[76:77], v[146:147], v[230:231]
	v_pk_fma_f32 v[74:75], v[74:75], v[144:145], v[228:229]
	global_store_dwordx4 v157, v[74:77], s[76:77] offset:64 nt
	global_load_dwordx4 v[228:231], v157, s[74:75] offset:576 nt
	s_waitcnt vmcnt(10)
	v_pk_fma_f32 v[72:73], v[72:73], v[150:151], v[234:235]
	v_pk_fma_f32 v[70:71], v[70:71], v[148:149], v[232:233]
	global_store_dwordx4 v157, v[70:73], s[76:77] offset:512 nt
	s_add_u32 s74, s74, 0x20000
	s_addc_u32 s75, s75, 0
	global_load_dwordx4 v[232:235], v157, s[74:75] nt
	s_waitcnt vmcnt(10)
	v_pk_fma_f32 v[68:69], v[68:69], v[170:171], v[238:239]
	v_pk_fma_f32 v[66:67], v[66:67], v[168:169], v[236:237]
	global_store_dwordx4 v157, v[66:69], s[76:77] offset:576 nt
	global_load_dwordx4 v[236:239], v157, s[74:75] offset:64 nt
	s_add_u32 s76, s76, 0xa0000
	s_addc_u32 s77, s77, 0
	s_waitcnt vmcnt(10)
	v_pk_fma_f32 v[64:65], v[64:65], v[142:143], v[242:243]
	v_pk_fma_f32 v[62:63], v[62:63], v[140:141], v[240:241]
	global_store_dwordx4 v157, v[62:65], s[76:77] nt
	global_load_dwordx4 v[240:243], v157, s[74:75] offset:512 nt
	s_waitcnt vmcnt(10)
	v_pk_fma_f32 v[60:61], v[60:61], v[146:147], v[246:247]
	v_pk_fma_f32 v[58:59], v[58:59], v[144:145], v[244:245]
	global_store_dwordx4 v157, v[58:61], s[76:77] offset:64 nt
	global_load_dwordx4 v[244:247], v157, s[74:75] offset:576 nt
	s_waitcnt vmcnt(10)
	v_pk_fma_f32 v[56:57], v[56:57], v[150:151], v[226:227]
	v_pk_fma_f32 v[54:55], v[54:55], v[148:149], v[224:225]
	global_store_dwordx4 v157, v[54:57], s[76:77] offset:512 nt
	s_add_u32 s74, s74, 0x20000
	s_addc_u32 s75, s75, 0
	global_load_dwordx4 v[224:227], v157, s[74:75] nt
	s_waitcnt vmcnt(10)
	v_pk_fma_f32 v[52:53], v[52:53], v[170:171], v[230:231]
	v_pk_fma_f32 v[50:51], v[50:51], v[168:169], v[228:229]
	global_store_dwordx4 v157, v[50:53], s[76:77] offset:576 nt
	global_load_dwordx4 v[228:231], v157, s[74:75] offset:64 nt
	s_add_u32 s76, s76, 0x20000
	s_addc_u32 s77, s77, 0
	s_waitcnt vmcnt(10)
	v_pk_fma_f32 v[48:49], v[48:49], v[142:143], v[234:235]
	v_pk_fma_f32 v[46:47], v[46:47], v[140:141], v[232:233]
	global_store_dwordx4 v157, v[46:49], s[76:77] nt
	global_load_dwordx4 v[232:235], v157, s[74:75] offset:512 nt
	s_waitcnt vmcnt(10)
	v_pk_fma_f32 v[44:45], v[44:45], v[146:147], v[238:239]
	v_pk_fma_f32 v[42:43], v[42:43], v[144:145], v[236:237]
	global_store_dwordx4 v157, v[42:45], s[76:77] offset:64 nt
	global_load_dwordx4 v[236:239], v157, s[74:75] offset:576 nt
	s_waitcnt vmcnt(10)
	v_pk_fma_f32 v[40:41], v[40:41], v[150:151], v[242:243]
	v_pk_fma_f32 v[38:39], v[38:39], v[148:149], v[240:241]
	global_store_dwordx4 v157, v[38:41], s[76:77] offset:512 nt
	s_add_u32 s74, s74, 0x20000
	s_addc_u32 s75, s75, 0
	global_load_dwordx4 v[240:243], v157, s[74:75] nt
	s_waitcnt vmcnt(10)
	v_pk_fma_f32 v[36:37], v[36:37], v[170:171], v[246:247]
	v_pk_fma_f32 v[34:35], v[34:35], v[168:169], v[244:245]
	global_store_dwordx4 v157, v[34:37], s[76:77] offset:576 nt
	global_load_dwordx4 v[244:247], v157, s[74:75] offset:64 nt
	s_add_u32 s76, s76, 0x20000
	s_addc_u32 s77, s77, 0
	s_waitcnt vmcnt(10)
	v_pk_fma_f32 v[32:33], v[32:33], v[142:143], v[226:227]
	v_pk_fma_f32 v[30:31], v[30:31], v[140:141], v[224:225]
	global_store_dwordx4 v157, v[30:33], s[76:77] nt
	global_load_dwordx4 v[224:227], v157, s[74:75] offset:512 nt
	s_waitcnt vmcnt(10)
	v_pk_fma_f32 v[28:29], v[28:29], v[146:147], v[230:231]
	v_pk_fma_f32 v[26:27], v[26:27], v[144:145], v[228:229]
	global_store_dwordx4 v157, v[26:29], s[76:77] offset:64 nt
	global_load_dwordx4 v[228:231], v157, s[74:75] offset:576 nt
	s_waitcnt vmcnt(10)
	v_pk_fma_f32 v[24:25], v[24:25], v[150:151], v[234:235]
	v_pk_fma_f32 v[22:23], v[22:23], v[148:149], v[232:233]
	global_store_dwordx4 v157, v[22:25], s[76:77] offset:512 nt
	s_waitcnt vmcnt(9)
	v_pk_fma_f32 v[20:21], v[20:21], v[170:171], v[238:239]
	v_pk_fma_f32 v[18:19], v[18:19], v[168:169], v[236:237]
	global_store_dwordx4 v157, v[18:21], s[76:77] offset:576 nt
	s_add_u32 s76, s76, 0x20000
	s_addc_u32 s77, s77, 0
	s_waitcnt vmcnt(8)
	v_pk_fma_f32 v[16:17], v[16:17], v[142:143], v[242:243]
	v_pk_fma_f32 v[14:15], v[14:15], v[140:141], v[240:241]
	global_store_dwordx4 v157, v[14:17], s[76:77] nt
	s_waitcnt vmcnt(7)
	v_pk_fma_f32 v[12:13], v[12:13], v[146:147], v[246:247]
	v_pk_fma_f32 v[10:11], v[10:11], v[144:145], v[244:245]
	global_store_dwordx4 v157, v[10:13], s[76:77] offset:64 nt
	s_waitcnt vmcnt(6)
	v_pk_fma_f32 v[8:9], v[8:9], v[150:151], v[226:227]
	v_pk_fma_f32 v[6:7], v[6:7], v[148:149], v[224:225]
	global_store_dwordx4 v157, v[6:9], s[76:77] offset:512 nt
	s_waitcnt vmcnt(5)
	v_pk_fma_f32 v[4:5], v[4:5], v[170:171], v[230:231]
	v_pk_fma_f32 v[2:3], v[2:3], v[168:169], v[228:229]
	global_store_dwordx4 v157, v[2:5], s[76:77] offset:576 nt
	s_branch .LBB0_24

.LBB0_234:
	s_add_u32 s39, s46, 0xfff80080
	s_addc_u32 s48, s47, -1
	s_add_i32 s62, 0, 0x10000
	ds_read_b128 v[144:147], v141
	ds_read_b128 v[148:151], v141 offset:1024
	ds_read_b128 v[152:155], v141 offset:2048
	ds_read_b128 v[168:171], v141 offset:3072
	s_cmp_eq_u32 s13, 28
	s_cselect_b32 s51, s43, s48
	s_cselect_b32 s50, s42, s39
	s_cselect_b32 s49, s45, s12
	s_cselect_b32 s48, s44, s1
	ds_read_b128 v[172:175], v143
	ds_read_b128 v[176:179], v143 offset:1024
	ds_read_b128 v[180:183], v143 offset:2048
	ds_read_b128 v[184:187], v143 offset:3072
	ds_read_b128 v[188:191], v143 offset:4096
	ds_read_b128 v[192:195], v143 offset:5120
	ds_read_b128 v[196:199], v143 offset:6144
	ds_read_b128 v[224:227], v143 offset:7168
	s_add_i32 m0, s53, 0xc000
	s_nop 0
	global_load_lds_dwordx4 v136, s[46:47]
	s_add_i32 m0, s53, 0xe000
	s_add_i32 s39, 0, 0x14000
	global_load_lds_dwordx4 v138, s[46:47]
	s_add_i32 s62, s62, s52
	ds_read_b128 v[228:231], v141 offset:16384
	ds_read_b128 v[232:235], v141 offset:17408
	ds_read_b128 v[236:239], v141 offset:18432
	ds_read_b128 v[240:243], v141 offset:19456
	s_waitcnt vmcnt(8) lgkmcnt(0)
	s_nop 0
	s_barrier
	v_mfma_f32_16x16x32_bf16 v[126:129], v[144:147], v[172:175], v[126:129]
	v_mfma_f32_16x16x32_bf16 v[122:125], v[152:155], v[172:175], v[122:125]
	v_mfma_f32_16x16x32_bf16 v[118:121], v[144:147], v[180:183], v[118:121]
	v_mfma_f32_16x16x32_bf16 v[114:117], v[152:155], v[180:183], v[114:117]
	v_mfma_f32_16x16x32_bf16 v[102:105], v[144:147], v[188:191], v[102:105]
	v_mfma_f32_16x16x32_bf16 v[98:101], v[152:155], v[188:191], v[98:101]
	v_mfma_f32_16x16x32_bf16 v[86:89], v[144:147], v[196:199], v[86:89]
	v_mfma_f32_16x16x32_bf16 v[82:85], v[152:155], v[196:199], v[82:85]
	v_mfma_f32_16x16x32_bf16 v[126:129], v[148:151], v[176:179], v[126:129]
	v_mfma_f32_16x16x32_bf16 v[122:125], v[168:171], v[176:179], v[122:125]
	v_mfma_f32_16x16x32_bf16 v[118:121], v[148:151], v[184:187], v[118:121]
	v_mfma_f32_16x16x32_bf16 v[114:117], v[168:171], v[184:187], v[114:117]
	v_mfma_f32_16x16x32_bf16 v[102:105], v[148:151], v[192:195], v[102:105]
	v_mfma_f32_16x16x32_bf16 v[98:101], v[168:171], v[192:195], v[98:101]
	v_mfma_f32_16x16x32_bf16 v[86:89], v[148:151], v[224:227], v[86:89]
	v_mfma_f32_16x16x32_bf16 v[82:85], v[168:171], v[224:227], v[82:85]
	v_mfma_f32_16x16x32_bf16 v[110:113], v[228:231], v[172:175], v[110:113]
	v_mfma_f32_16x16x32_bf16 v[106:109], v[236:239], v[172:175], v[106:109]
	v_mfma_f32_16x16x32_bf16 v[94:97], v[228:231], v[180:183], v[94:97]
	v_mfma_f32_16x16x32_bf16 v[90:93], v[236:239], v[180:183], v[90:93]
	v_mfma_f32_16x16x32_bf16 v[78:81], v[228:231], v[188:191], v[78:81]
	v_mfma_f32_16x16x32_bf16 v[74:77], v[236:239], v[188:191], v[74:77]
	v_mfma_f32_16x16x32_bf16 v[70:73], v[228:231], v[196:199], v[70:73]
	v_mfma_f32_16x16x32_bf16 v[66:69], v[236:239], v[196:199], v[66:69]
	v_mfma_f32_16x16x32_bf16 v[110:113], v[232:235], v[176:179], v[110:113]
	v_mfma_f32_16x16x32_bf16 v[106:109], v[240:243], v[176:179], v[106:109]
	v_mfma_f32_16x16x32_bf16 v[94:97], v[232:235], v[184:187], v[94:97]
	v_mfma_f32_16x16x32_bf16 v[90:93], v[240:243], v[184:187], v[90:93]
	v_mfma_f32_16x16x32_bf16 v[78:81], v[232:235], v[192:195], v[78:81]
	v_mfma_f32_16x16x32_bf16 v[74:77], v[240:243], v[192:195], v[74:77]
	v_mfma_f32_16x16x32_bf16 v[70:73], v[232:235], v[224:227], v[70:73]
	v_mfma_f32_16x16x32_bf16 v[66:69], v[240:243], v[224:227], v[66:69]
	s_barrier
	s_mov_b32 m0, s53
	s_add_u32 s78, s50, s94
	s_addc_u32 s79, s51, s95
	ds_read_b128 v[172:175], v143 offset:16384
	ds_read_b128 v[176:179], v143 offset:17408
	ds_read_b128 v[180:183], v143 offset:18432
	ds_read_b128 v[184:187], v143 offset:19456
	ds_read_b128 v[188:191], v143 offset:20480
	ds_read_b128 v[192:195], v143 offset:21504
	ds_read_b128 v[196:199], v143 offset:22528
	ds_read_b128 v[224:227], v143 offset:23552
	global_load_lds_dwordx4 v134, s[50:51]
	s_mov_b32 m0, s54
	s_add_u32 s76, s48, s94
	s_addc_u32 s77, s49, s95
	global_load_lds_dwordx4 v132, s[50:51]
	s_mov_b32 m0, s62
	s_nop 0
	global_load_lds_dwordx4 v0, s[48:49]
	s_add_i32 m0, s62, 0x2000
	s_add_u32 s62, s48, 0x80000
	s_addc_u32 s63, s49, 0
	global_load_lds_dwordx4 v130, s[48:49]
	s_add_i32 s39, s39, s52
	s_mov_b32 m0, s39
	s_nop 0
	global_load_lds_dwordx4 v0, s[62:63]
	s_add_i32 m0, s39, 0x2000
	s_nop 0
	global_load_lds_dwordx4 v130, s[62:63]
	s_waitcnt vmcnt(8) lgkmcnt(0)
	s_barrier
	v_mfma_f32_16x16x32_bf16 v[62:65], v[144:147], v[172:175], v[62:65]
	v_mfma_f32_16x16x32_bf16 v[58:61], v[152:155], v[172:175], v[58:61]
	v_mfma_f32_16x16x32_bf16 v[54:57], v[144:147], v[180:183], v[54:57]
	v_mfma_f32_16x16x32_bf16 v[50:53], v[152:155], v[180:183], v[50:53]
	v_mfma_f32_16x16x32_bf16 v[38:41], v[144:147], v[188:191], v[38:41]
	v_mfma_f32_16x16x32_bf16 v[34:37], v[152:155], v[188:191], v[34:37]
	v_mfma_f32_16x16x32_bf16 v[22:25], v[144:147], v[196:199], v[22:25]
	v_mfma_f32_16x16x32_bf16 v[18:21], v[152:155], v[196:199], v[18:21]
	v_mfma_f32_16x16x32_bf16 v[62:65], v[148:151], v[176:179], v[62:65]
	v_mfma_f32_16x16x32_bf16 v[58:61], v[168:171], v[176:179], v[58:61]
	v_mfma_f32_16x16x32_bf16 v[54:57], v[148:151], v[184:187], v[54:57]
	v_mfma_f32_16x16x32_bf16 v[50:53], v[168:171], v[184:187], v[50:53]
	v_mfma_f32_16x16x32_bf16 v[38:41], v[148:151], v[192:195], v[38:41]
	v_mfma_f32_16x16x32_bf16 v[34:37], v[168:171], v[192:195], v[34:37]
	v_mfma_f32_16x16x32_bf16 v[22:25], v[148:151], v[224:227], v[22:25]
	v_mfma_f32_16x16x32_bf16 v[18:21], v[168:171], v[224:227], v[18:21]
	v_mfma_f32_16x16x32_bf16 v[46:49], v[228:231], v[172:175], v[46:49]
	v_mfma_f32_16x16x32_bf16 v[42:45], v[236:239], v[172:175], v[42:45]
	v_mfma_f32_16x16x32_bf16 v[30:33], v[228:231], v[180:183], v[30:33]
	v_mfma_f32_16x16x32_bf16 v[26:29], v[236:239], v[180:183], v[26:29]
	v_mfma_f32_16x16x32_bf16 v[14:17], v[228:231], v[188:191], v[14:17]
	v_mfma_f32_16x16x32_bf16 v[10:13], v[236:239], v[188:191], v[10:13]
	v_mfma_f32_16x16x32_bf16 v[6:9], v[228:231], v[196:199], v[6:9]
	v_mfma_f32_16x16x32_bf16 v[2:5], v[236:239], v[196:199], v[2:5]
	v_mfma_f32_16x16x32_bf16 v[46:49], v[232:235], v[176:179], v[46:49]
	v_mfma_f32_16x16x32_bf16 v[42:45], v[240:243], v[176:179], v[42:45]
	v_mfma_f32_16x16x32_bf16 v[30:33], v[232:235], v[184:187], v[30:33]
	v_mfma_f32_16x16x32_bf16 v[26:29], v[240:243], v[184:187], v[26:29]
	v_mfma_f32_16x16x32_bf16 v[14:17], v[232:235], v[192:195], v[14:17]
	v_mfma_f32_16x16x32_bf16 v[10:13], v[240:243], v[192:195], v[10:13]
	v_mfma_f32_16x16x32_bf16 v[6:9], v[232:235], v[224:227], v[6:9]
	v_mfma_f32_16x16x32_bf16 v[2:5], v[240:243], v[224:227], v[2:5]
	s_barrier
	s_add_i32 s39, 0, 0x18000
	ds_read_b128 v[144:147], v141 offset:32768
	ds_read_b128 v[148:151], v141 offset:33792
	ds_read_b128 v[152:155], v141 offset:34816
	ds_read_b128 v[168:171], v141 offset:35840
	s_add_u32 s50, s50, 0x80000
	s_addc_u32 s51, s51, 0
	ds_read_b128 v[172:175], v143 offset:32768
	ds_read_b128 v[176:179], v143 offset:33792
	ds_read_b128 v[180:183], v143 offset:34816
	ds_read_b128 v[184:187], v143 offset:35840
	ds_read_b128 v[188:191], v143 offset:36864
	ds_read_b128 v[192:195], v143 offset:37888
	ds_read_b128 v[196:199], v143 offset:38912
	ds_read_b128 v[224:227], v143 offset:39936
	s_mov_b32 m0, s55
	s_nop 0
	global_load_lds_dwordx4 v134, s[50:51]
	s_mov_b32 m0, s56
	s_nop 0
	global_load_lds_dwordx4 v132, s[50:51]
	s_add_i32 s50, 0, 0x1c000
	s_add_i32 s39, s39, s52
	ds_read_b128 v[228:231], v141 offset:49152
	ds_read_b128 v[232:235], v141 offset:50176
	ds_read_b128 v[236:239], v141 offset:51200
	ds_read_b128 v[240:243], v141 offset:52224
	s_waitcnt vmcnt(8) lgkmcnt(0)
	s_nop 0
	s_barrier
	v_mfma_f32_16x16x32_bf16 v[126:129], v[144:147], v[172:175], v[126:129]
	v_mfma_f32_16x16x32_bf16 v[122:125], v[152:155], v[172:175], v[122:125]
	v_mfma_f32_16x16x32_bf16 v[118:121], v[144:147], v[180:183], v[118:121]
	v_mfma_f32_16x16x32_bf16 v[114:117], v[152:155], v[180:183], v[114:117]
	v_mfma_f32_16x16x32_bf16 v[102:105], v[144:147], v[188:191], v[102:105]
	v_mfma_f32_16x16x32_bf16 v[98:101], v[152:155], v[188:191], v[98:101]
	v_mfma_f32_16x16x32_bf16 v[86:89], v[144:147], v[196:199], v[86:89]
	v_mfma_f32_16x16x32_bf16 v[82:85], v[152:155], v[196:199], v[82:85]
	v_mfma_f32_16x16x32_bf16 v[126:129], v[148:151], v[176:179], v[126:129]
	v_mfma_f32_16x16x32_bf16 v[122:125], v[168:171], v[176:179], v[122:125]
	v_mfma_f32_16x16x32_bf16 v[118:121], v[148:151], v[184:187], v[118:121]
	v_mfma_f32_16x16x32_bf16 v[114:117], v[168:171], v[184:187], v[114:117]
	v_mfma_f32_16x16x32_bf16 v[102:105], v[148:151], v[192:195], v[102:105]
	v_mfma_f32_16x16x32_bf16 v[98:101], v[168:171], v[192:195], v[98:101]
	v_mfma_f32_16x16x32_bf16 v[86:89], v[148:151], v[224:227], v[86:89]
	v_mfma_f32_16x16x32_bf16 v[82:85], v[168:171], v[224:227], v[82:85]
	v_mfma_f32_16x16x32_bf16 v[110:113], v[228:231], v[172:175], v[110:113]
	v_mfma_f32_16x16x32_bf16 v[106:109], v[236:239], v[172:175], v[106:109]
	v_mfma_f32_16x16x32_bf16 v[94:97], v[228:231], v[180:183], v[94:97]
	v_mfma_f32_16x16x32_bf16 v[90:93], v[236:239], v[180:183], v[90:93]
	v_mfma_f32_16x16x32_bf16 v[78:81], v[228:231], v[188:191], v[78:81]
	v_mfma_f32_16x16x32_bf16 v[74:77], v[236:239], v[188:191], v[74:77]
	v_mfma_f32_16x16x32_bf16 v[70:73], v[228:231], v[196:199], v[70:73]
	v_mfma_f32_16x16x32_bf16 v[66:69], v[236:239], v[196:199], v[66:69]
	v_mfma_f32_16x16x32_bf16 v[110:113], v[232:235], v[176:179], v[110:113]
	v_mfma_f32_16x16x32_bf16 v[106:109], v[240:243], v[176:179], v[106:109]
	v_mfma_f32_16x16x32_bf16 v[94:97], v[232:235], v[184:187], v[94:97]
	v_mfma_f32_16x16x32_bf16 v[90:93], v[240:243], v[184:187], v[90:93]
	v_mfma_f32_16x16x32_bf16 v[78:81], v[232:235], v[192:195], v[78:81]
	v_mfma_f32_16x16x32_bf16 v[74:77], v[240:243], v[192:195], v[74:77]
	v_mfma_f32_16x16x32_bf16 v[70:73], v[232:235], v[224:227], v[70:73]
	v_mfma_f32_16x16x32_bf16 v[66:69], v[240:243], v[224:227], v[66:69]
	s_barrier
	s_mov_b32 m0, s57
	ds_read_b128 v[172:175], v143 offset:49152
	ds_read_b128 v[176:179], v143 offset:50176
	ds_read_b128 v[180:183], v143 offset:51200
	ds_read_b128 v[184:187], v143 offset:52224
	ds_read_b128 v[188:191], v143 offset:53248
	ds_read_b128 v[192:195], v143 offset:54272
	ds_read_b128 v[196:199], v143 offset:55296
	ds_read_b128 v[224:227], v143 offset:56320
	global_load_lds_dwordx4 v134, s[78:79]
	s_mov_b32 m0, s58
	s_nop 0
	global_load_lds_dwordx4 v132, s[78:79]
	s_mov_b32 m0, s39
	s_nop 0
	global_load_lds_dwordx4 v0, s[76:77]
	s_add_i32 m0, s39, 0x2000
	s_add_u32 s48, s48, 0x80080
	s_addc_u32 s49, s49, 0
	global_load_lds_dwordx4 v130, s[76:77]
	s_add_i32 s39, s50, s52
	s_mov_b32 m0, s39
	s_nop 0
	global_load_lds_dwordx4 v0, s[48:49]
	s_add_i32 m0, s39, 0x2000
	s_nop 0
	global_load_lds_dwordx4 v130, s[48:49]
	s_waitcnt vmcnt(8) lgkmcnt(0)
	s_nop 0
	s_barrier
	v_mfma_f32_16x16x32_bf16 v[62:65], v[144:147], v[172:175], v[62:65]
	v_mfma_f32_16x16x32_bf16 v[58:61], v[152:155], v[172:175], v[58:61]
	v_mfma_f32_16x16x32_bf16 v[54:57], v[144:147], v[180:183], v[54:57]
	v_mfma_f32_16x16x32_bf16 v[50:53], v[152:155], v[180:183], v[50:53]
	v_mfma_f32_16x16x32_bf16 v[38:41], v[144:147], v[188:191], v[38:41]
	v_mfma_f32_16x16x32_bf16 v[34:37], v[152:155], v[188:191], v[34:37]
	v_mfma_f32_16x16x32_bf16 v[22:25], v[144:147], v[196:199], v[22:25]
	v_mfma_f32_16x16x32_bf16 v[18:21], v[152:155], v[196:199], v[18:21]
	v_mfma_f32_16x16x32_bf16 v[62:65], v[148:151], v[176:179], v[62:65]
	v_mfma_f32_16x16x32_bf16 v[58:61], v[168:171], v[176:179], v[58:61]
	v_mfma_f32_16x16x32_bf16 v[54:57], v[148:151], v[184:187], v[54:57]
	v_mfma_f32_16x16x32_bf16 v[50:53], v[168:171], v[184:187], v[50:53]
	v_mfma_f32_16x16x32_bf16 v[38:41], v[148:151], v[192:195], v[38:41]
	v_mfma_f32_16x16x32_bf16 v[34:37], v[168:171], v[192:195], v[34:37]
	v_mfma_f32_16x16x32_bf16 v[22:25], v[148:151], v[224:227], v[22:25]
	v_mfma_f32_16x16x32_bf16 v[18:21], v[168:171], v[224:227], v[18:21]
	v_mfma_f32_16x16x32_bf16 v[46:49], v[228:231], v[172:175], v[46:49]
	v_mfma_f32_16x16x32_bf16 v[42:45], v[236:239], v[172:175], v[42:45]
	v_mfma_f32_16x16x32_bf16 v[30:33], v[228:231], v[180:183], v[30:33]
	v_mfma_f32_16x16x32_bf16 v[26:29], v[236:239], v[180:183], v[26:29]
	v_mfma_f32_16x16x32_bf16 v[14:17], v[228:231], v[188:191], v[14:17]
	v_mfma_f32_16x16x32_bf16 v[10:13], v[236:239], v[188:191], v[10:13]
	v_mfma_f32_16x16x32_bf16 v[6:9], v[228:231], v[196:199], v[6:9]
	v_mfma_f32_16x16x32_bf16 v[2:5], v[236:239], v[196:199], v[2:5]
	v_mfma_f32_16x16x32_bf16 v[46:49], v[232:235], v[176:179], v[46:49]
	v_mfma_f32_16x16x32_bf16 v[42:45], v[240:243], v[176:179], v[42:45]
	v_mfma_f32_16x16x32_bf16 v[30:33], v[232:235], v[184:187], v[30:33]
	v_mfma_f32_16x16x32_bf16 v[26:29], v[240:243], v[184:187], v[26:29]
	v_mfma_f32_16x16x32_bf16 v[14:17], v[232:235], v[192:195], v[14:17]
	v_mfma_f32_16x16x32_bf16 v[10:13], v[240:243], v[192:195], v[10:13]
	v_mfma_f32_16x16x32_bf16 v[6:9], v[232:235], v[224:227], v[6:9]
	v_mfma_f32_16x16x32_bf16 v[2:5], v[240:243], v[224:227], v[2:5]
	s_barrier
	s_add_i32 s13, s13, 2
	s_add_u32 s46, s46, 0x100
	s_addc_u32 s47, s47, 0
	s_add_u32 s1, s1, 0x100
	s_addc_u32 s12, s12, 0
	s_cmp_gt_u32 s13, 29
	s_cbranch_scc0 .LBB0_234
	v_readlane_b32 s6, v255, 23
	v_lshl_add_u32 v150, s61, 8, v140
	v_lshl_or_b32 v144, s60, 8, v142
	v_readlane_b32 s7, v255, 24
	v_ashrrev_i32_e32 v145, 31, v144
	s_movk_i32 s1, 0x5800
	v_mov_b64_e32 v[146:147], s[6:7]
	v_cvt_pk_bf16_f32 v70, v70, v71
	v_cvt_pk_bf16_f32 v71, v72, v73
	v_cvt_pk_bf16_f32 v72, v66, v67
	v_add_u32_e32 v66, 0x80, v150
	v_mad_i64_i32 v[148:149], s[12:13], v150, s1, v[146:147]
	v_lshlrev_b64 v[144:145], 1, v[144:145]
	v_cvt_pk_bf16_f32 v110, v110, v111
	v_cvt_pk_bf16_f32 v111, v112, v113
	v_cvt_pk_bf16_f32 v112, v106, v107
	v_or_b32_e32 v106, 16, v150
	v_mad_i64_i32 v[66:67], s[12:13], v66, s1, v[146:147]
	v_cvt_pk_bf16_f32 v46, v46, v47
	v_cvt_pk_bf16_f32 v47, v48, v49
	v_cvt_pk_bf16_f32 v48, v42, v43
	v_add_u32_e32 v42, 0x90, v150
	v_lshl_add_u64 v[148:149], v[148:149], 0, v[144:145]
	v_cvt_pk_bf16_f32 v113, v108, v109
	v_mad_i64_i32 v[106:107], s[12:13], v106, s1, v[146:147]
	v_cvt_pk_bf16_f32 v94, v94, v95
	v_cvt_pk_bf16_f32 v95, v96, v97
	v_cvt_pk_bf16_f32 v96, v90, v91
	v_or_b32_e32 v90, 32, v150
	v_lshl_add_u64 v[66:67], v[66:67], 0, v[144:145]
	v_cvt_pk_bf16_f32 v49, v44, v45
	v_mad_i64_i32 v[42:43], s[12:13], v42, s1, v[146:147]
	v_cvt_pk_bf16_f32 v30, v30, v31
	v_cvt_pk_bf16_f32 v31, v32, v33
	v_cvt_pk_bf16_f32 v32, v26, v27
	v_add_u32_e32 v26, 0xa0, v150
	global_store_dwordx4 v[148:149], v[110:113], off offset:256
	v_cvt_pk_bf16_f32 v97, v92, v93
	v_mad_i64_i32 v[90:91], s[12:13], v90, s1, v[146:147]
	v_lshl_add_u64 v[110:111], v[106:107], 0, v[144:145]
	v_cvt_pk_bf16_f32 v78, v78, v79
	v_cvt_pk_bf16_f32 v79, v80, v81
	v_cvt_pk_bf16_f32 v80, v74, v75
	v_or_b32_e32 v74, 48, v150
	global_store_dwordx4 v[66:67], v[46:49], off offset:256
	v_cvt_pk_bf16_f32 v33, v28, v29
	v_mad_i64_i32 v[26:27], s[12:13], v26, s1, v[146:147]
	v_lshl_add_u64 v[46:47], v[42:43], 0, v[144:145]
	v_cvt_pk_bf16_f32 v14, v14, v15
	v_cvt_pk_bf16_f32 v15, v16, v17
	v_cvt_pk_bf16_f32 v16, v10, v11
	v_add_u32_e32 v10, 0xb0, v150
	global_store_dwordx4 v[110:111], v[94:97], off offset:256
	v_cvt_pk_bf16_f32 v81, v76, v77
	v_mad_i64_i32 v[74:75], s[12:13], v74, s1, v[146:147]
	v_lshl_add_u64 v[94:95], v[90:91], 0, v[144:145]
	global_store_dwordx4 v[46:47], v[30:33], off offset:256
	v_cvt_pk_bf16_f32 v17, v12, v13
	v_mad_i64_i32 v[10:11], s[12:13], v10, s1, v[146:147]
	v_lshl_add_u64 v[30:31], v[26:27], 0, v[144:145]
	v_cvt_pk_bf16_f32 v126, v126, v127
	v_cvt_pk_bf16_f32 v127, v128, v129
	v_cvt_pk_bf16_f32 v128, v122, v123
	v_cvt_pk_bf16_f32 v129, v124, v125
	v_cvt_pk_bf16_f32 v106, v118, v119
	v_cvt_pk_bf16_f32 v107, v120, v121
	v_cvt_pk_bf16_f32 v108, v114, v115
	v_cvt_pk_bf16_f32 v109, v116, v117
	v_cvt_pk_bf16_f32 v90, v102, v103
	v_cvt_pk_bf16_f32 v91, v104, v105
	v_cvt_pk_bf16_f32 v92, v98, v99
	v_cvt_pk_bf16_f32 v93, v100, v101
	global_store_dwordx4 v[94:95], v[78:81], off offset:256
	v_cvt_pk_bf16_f32 v76, v82, v83
	v_cvt_pk_bf16_f32 v77, v84, v85
	v_lshl_add_u64 v[78:79], v[74:75], 0, v[144:145]
	v_cvt_pk_bf16_f32 v74, v86, v87
	v_cvt_pk_bf16_f32 v75, v88, v89
	v_cvt_pk_bf16_f32 v73, v68, v69
	v_cvt_pk_bf16_f32 v62, v62, v63
	v_cvt_pk_bf16_f32 v63, v64, v65
	v_cvt_pk_bf16_f32 v64, v58, v59
	v_cvt_pk_bf16_f32 v65, v60, v61
	v_cvt_pk_bf16_f32 v42, v54, v55
	v_cvt_pk_bf16_f32 v43, v56, v57
	v_cvt_pk_bf16_f32 v44, v50, v51
	v_cvt_pk_bf16_f32 v45, v52, v53
	v_cvt_pk_bf16_f32 v26, v38, v39
	v_cvt_pk_bf16_f32 v27, v40, v41
	v_cvt_pk_bf16_f32 v28, v34, v35
	v_cvt_pk_bf16_f32 v29, v36, v37
	global_store_dwordx4 v[30:31], v[14:17], off offset:256
	v_cvt_pk_bf16_f32 v12, v18, v19
	v_cvt_pk_bf16_f32 v13, v20, v21
	v_lshl_add_u64 v[14:15], v[10:11], 0, v[144:145]
	v_cvt_pk_bf16_f32 v10, v22, v23
	v_cvt_pk_bf16_f32 v11, v24, v25
	v_cvt_pk_bf16_f32 v6, v6, v7
	v_cvt_pk_bf16_f32 v7, v8, v9
	v_cvt_pk_bf16_f32 v8, v2, v3
	v_cvt_pk_bf16_f32 v9, v4, v5
	s_and_b64 vcc, exec, s[40:41]
	s_mov_b32 s60, s0
	s_mov_b32 s61, s38
	s_mov_b64 s[48:49], s[44:45]
	s_mov_b64 s[46:47], s[42:43]
	global_store_dwordx4 v[148:149], v[126:129], off
	global_store_dwordx4 v[110:111], v[106:109], off
	global_store_dwordx4 v[94:95], v[90:93], off
	global_store_dwordx4 v[78:79], v[74:77], off
	global_store_dwordx4 v[78:79], v[70:73], off offset:256
	global_store_dwordx4 v[66:67], v[62:65], off
	global_store_dwordx4 v[46:47], v[42:45], off
	global_store_dwordx4 v[30:31], v[26:29], off
	global_store_dwordx4 v[14:15], v[10:13], off
	global_store_dwordx4 v[14:15], v[6:9], off offset:256
	s_cbranch_vccz .LBB0_227
	s_waitcnt vmcnt(0)
	v_readlane_b32 s60, v255, 21
	s_cmpk_gt_u32 s36, 0xff
	s_mov_b32 s18, s60
	v_readlane_b32 s61, v255, 22
	s_cbranch_scc1 .LBB0_238
	s_barrier

.LBB0_282:
	s_add_i32 s67, s50, 2
	s_add_u32 s51, s0, 0xfff80080
	s_addc_u32 s52, s1, -1
	s_add_i32 s68, 0, 0x10000
	ds_read_b128 v[136:139], v153
	ds_read_b128 v[140:143], v153 offset:1024
	ds_read_b128 v[144:147], v153 offset:2048
	ds_read_b128 v[148:151], v153 offset:3072
	s_cmp_eq_u32 s12, s50
	s_cselect_b32 s50, s48, s13
	s_cselect_b32 s53, s47, s52
	s_cselect_b32 s52, s46, s51
	s_cselect_b32 s51, s49, s66
	ds_read_b128 v[168:171], v155
	ds_read_b128 v[172:175], v155 offset:1024
	ds_read_b128 v[176:179], v155 offset:2048
	ds_read_b128 v[180:183], v155 offset:3072
	ds_read_b128 v[184:187], v155 offset:4096
	ds_read_b128 v[188:191], v155 offset:5120
	ds_read_b128 v[192:195], v155 offset:6144
	ds_read_b128 v[196:199], v155 offset:7168
	s_add_i32 m0, s55, 0xc000
	s_nop 0
	global_load_lds_dwordx4 v132, s[0:1]
	s_add_i32 m0, s55, 0xe000
	s_add_i32 s70, 0, 0x14000
	global_load_lds_dwordx4 v134, s[0:1]
	s_add_i32 s68, s68, s54
	ds_read_b128 v[224:227], v153 offset:16384
	ds_read_b128 v[228:231], v153 offset:17408
	ds_read_b128 v[232:235], v153 offset:18432
	ds_read_b128 v[236:239], v153 offset:19456
	s_waitcnt vmcnt(8) lgkmcnt(0)
	s_barrier
	v_mfma_f32_16x16x32_bf16 v[126:129], v[136:139], v[168:171], v[126:129]
	v_mfma_f32_16x16x32_bf16 v[122:125], v[144:147], v[168:171], v[122:125]
	v_mfma_f32_16x16x32_bf16 v[110:113], v[136:139], v[176:179], v[110:113]
	v_mfma_f32_16x16x32_bf16 v[106:109], v[144:147], v[176:179], v[106:109]
	v_mfma_f32_16x16x32_bf16 v[94:97], v[136:139], v[184:187], v[94:97]
	v_mfma_f32_16x16x32_bf16 v[90:93], v[144:147], v[184:187], v[90:93]
	v_mfma_f32_16x16x32_bf16 v[78:81], v[136:139], v[192:195], v[78:81]
	v_mfma_f32_16x16x32_bf16 v[74:77], v[144:147], v[192:195], v[74:77]
	v_mfma_f32_16x16x32_bf16 v[126:129], v[140:143], v[172:175], v[126:129]
	v_mfma_f32_16x16x32_bf16 v[122:125], v[148:151], v[172:175], v[122:125]
	v_mfma_f32_16x16x32_bf16 v[110:113], v[140:143], v[180:183], v[110:113]
	v_mfma_f32_16x16x32_bf16 v[106:109], v[148:151], v[180:183], v[106:109]
	v_mfma_f32_16x16x32_bf16 v[94:97], v[140:143], v[188:191], v[94:97]
	v_mfma_f32_16x16x32_bf16 v[90:93], v[148:151], v[188:191], v[90:93]
	v_mfma_f32_16x16x32_bf16 v[78:81], v[140:143], v[196:199], v[78:81]
	v_mfma_f32_16x16x32_bf16 v[74:77], v[148:151], v[196:199], v[74:77]
	v_mfma_f32_16x16x32_bf16 v[118:121], v[224:227], v[168:171], v[118:121]
	v_mfma_f32_16x16x32_bf16 v[114:117], v[232:235], v[168:171], v[114:117]
	v_mfma_f32_16x16x32_bf16 v[102:105], v[224:227], v[176:179], v[102:105]
	v_mfma_f32_16x16x32_bf16 v[98:101], v[232:235], v[176:179], v[98:101]
	v_mfma_f32_16x16x32_bf16 v[86:89], v[224:227], v[184:187], v[86:89]
	v_mfma_f32_16x16x32_bf16 v[82:85], v[232:235], v[184:187], v[82:85]
	v_mfma_f32_16x16x32_bf16 v[70:73], v[224:227], v[192:195], v[70:73]
	v_mfma_f32_16x16x32_bf16 v[66:69], v[232:235], v[192:195], v[66:69]
	v_mfma_f32_16x16x32_bf16 v[118:121], v[228:231], v[172:175], v[118:121]
	v_mfma_f32_16x16x32_bf16 v[114:117], v[236:239], v[172:175], v[114:117]
	v_mfma_f32_16x16x32_bf16 v[102:105], v[228:231], v[180:183], v[102:105]
	v_mfma_f32_16x16x32_bf16 v[98:101], v[236:239], v[180:183], v[98:101]
	v_mfma_f32_16x16x32_bf16 v[86:89], v[228:231], v[188:191], v[86:89]
	v_mfma_f32_16x16x32_bf16 v[82:85], v[236:239], v[188:191], v[82:85]
	v_mfma_f32_16x16x32_bf16 v[70:73], v[228:231], v[196:199], v[70:73]
	v_mfma_f32_16x16x32_bf16 v[66:69], v[236:239], v[196:199], v[66:69]
	s_barrier
	s_mov_b32 m0, s55
	s_add_u32 s78, s52, s94
	s_addc_u32 s79, s53, s95
	ds_read_b128 v[168:171], v155 offset:16384
	ds_read_b128 v[172:175], v155 offset:17408
	ds_read_b128 v[176:179], v155 offset:18432
	ds_read_b128 v[180:183], v155 offset:19456
	ds_read_b128 v[184:187], v155 offset:20480
	ds_read_b128 v[188:191], v155 offset:21504
	ds_read_b128 v[192:195], v155 offset:22528
	ds_read_b128 v[196:199], v155 offset:23552
	global_load_lds_dwordx4 v0, s[52:53]
	s_mov_b32 m0, s56
	s_add_u32 s76, s50, s94
	s_addc_u32 s77, s51, s95
	global_load_lds_dwordx4 v130, s[52:53]
	s_mov_b32 m0, s68
	s_nop 0
	global_load_lds_dwordx4 v0, s[50:51]
	s_add_i32 m0, s68, 0x2000
	s_add_u32 s68, s50, 0x80000
	s_addc_u32 s69, s51, 0
	global_load_lds_dwordx4 v130, s[50:51]
	s_add_i32 s70, s70, s54
	s_mov_b32 m0, s70
	s_nop 0
	global_load_lds_dwordx4 v0, s[68:69]
	s_add_i32 m0, s70, 0x2000
	s_nop 0
	global_load_lds_dwordx4 v130, s[68:69]
	s_waitcnt vmcnt(8) lgkmcnt(0)
	s_barrier
	v_mfma_f32_16x16x32_bf16 v[62:65], v[136:139], v[168:171], v[62:65]
	v_mfma_f32_16x16x32_bf16 v[58:61], v[144:147], v[168:171], v[58:61]
	v_mfma_f32_16x16x32_bf16 v[46:49], v[136:139], v[176:179], v[46:49]
	v_mfma_f32_16x16x32_bf16 v[42:45], v[144:147], v[176:179], v[42:45]
	v_mfma_f32_16x16x32_bf16 v[30:33], v[136:139], v[184:187], v[30:33]
	v_mfma_f32_16x16x32_bf16 v[26:29], v[144:147], v[184:187], v[26:29]
	v_mfma_f32_16x16x32_bf16 v[14:17], v[136:139], v[192:195], v[14:17]
	v_mfma_f32_16x16x32_bf16 v[10:13], v[144:147], v[192:195], v[10:13]
	v_mfma_f32_16x16x32_bf16 v[62:65], v[140:143], v[172:175], v[62:65]
	v_mfma_f32_16x16x32_bf16 v[58:61], v[148:151], v[172:175], v[58:61]
	v_mfma_f32_16x16x32_bf16 v[46:49], v[140:143], v[180:183], v[46:49]
	v_mfma_f32_16x16x32_bf16 v[42:45], v[148:151], v[180:183], v[42:45]
	v_mfma_f32_16x16x32_bf16 v[30:33], v[140:143], v[188:191], v[30:33]
	v_mfma_f32_16x16x32_bf16 v[26:29], v[148:151], v[188:191], v[26:29]
	v_mfma_f32_16x16x32_bf16 v[14:17], v[140:143], v[196:199], v[14:17]
	v_mfma_f32_16x16x32_bf16 v[10:13], v[148:151], v[196:199], v[10:13]
	v_mfma_f32_16x16x32_bf16 v[54:57], v[224:227], v[168:171], v[54:57]
	v_mfma_f32_16x16x32_bf16 v[50:53], v[232:235], v[168:171], v[50:53]
	v_mfma_f32_16x16x32_bf16 v[38:41], v[224:227], v[176:179], v[38:41]
	v_mfma_f32_16x16x32_bf16 v[34:37], v[232:235], v[176:179], v[34:37]
	v_mfma_f32_16x16x32_bf16 v[22:25], v[224:227], v[184:187], v[22:25]
	v_mfma_f32_16x16x32_bf16 v[18:21], v[232:235], v[184:187], v[18:21]
	v_mfma_f32_16x16x32_bf16 v[6:9], v[224:227], v[192:195], v[6:9]
	v_mfma_f32_16x16x32_bf16 v[2:5], v[232:235], v[192:195], v[2:5]
	v_mfma_f32_16x16x32_bf16 v[54:57], v[228:231], v[172:175], v[54:57]
	v_mfma_f32_16x16x32_bf16 v[50:53], v[236:239], v[172:175], v[50:53]
	v_mfma_f32_16x16x32_bf16 v[38:41], v[228:231], v[180:183], v[38:41]
	v_mfma_f32_16x16x32_bf16 v[34:37], v[236:239], v[180:183], v[34:37]
	v_mfma_f32_16x16x32_bf16 v[22:25], v[228:231], v[188:191], v[22:25]
	v_mfma_f32_16x16x32_bf16 v[18:21], v[236:239], v[188:191], v[18:21]
	v_mfma_f32_16x16x32_bf16 v[6:9], v[228:231], v[196:199], v[6:9]
	v_mfma_f32_16x16x32_bf16 v[2:5], v[236:239], v[196:199], v[2:5]
	s_barrier
	s_add_i32 s68, 0, 0x18000
	ds_read_b128 v[136:139], v153 offset:32768
	ds_read_b128 v[140:143], v153 offset:33792
	ds_read_b128 v[144:147], v153 offset:34816
	ds_read_b128 v[148:151], v153 offset:35840
	s_add_u32 s52, s52, 0x80000
	s_addc_u32 s53, s53, 0
	ds_read_b128 v[168:171], v155 offset:32768
	ds_read_b128 v[172:175], v155 offset:33792
	ds_read_b128 v[176:179], v155 offset:34816
	ds_read_b128 v[180:183], v155 offset:35840
	ds_read_b128 v[184:187], v155 offset:36864
	ds_read_b128 v[188:191], v155 offset:37888
	ds_read_b128 v[192:195], v155 offset:38912
	ds_read_b128 v[196:199], v155 offset:39936
	s_mov_b32 m0, s57
	s_nop 0
	global_load_lds_dwordx4 v0, s[52:53]
	s_mov_b32 m0, s58
	s_nop 0
	global_load_lds_dwordx4 v130, s[52:53]
	s_add_i32 s52, 0, 0x1c000
	s_add_i32 s53, s68, s54
	ds_read_b128 v[224:227], v153 offset:49152
	ds_read_b128 v[228:231], v153 offset:50176
	ds_read_b128 v[232:235], v153 offset:51200
	ds_read_b128 v[236:239], v153 offset:52224
	s_waitcnt vmcnt(8) lgkmcnt(0)
	s_nop 0
	s_barrier
	v_mfma_f32_16x16x32_bf16 v[126:129], v[136:139], v[168:171], v[126:129]
	v_mfma_f32_16x16x32_bf16 v[122:125], v[144:147], v[168:171], v[122:125]
	v_mfma_f32_16x16x32_bf16 v[110:113], v[136:139], v[176:179], v[110:113]
	v_mfma_f32_16x16x32_bf16 v[106:109], v[144:147], v[176:179], v[106:109]
	v_mfma_f32_16x16x32_bf16 v[94:97], v[136:139], v[184:187], v[94:97]
	v_mfma_f32_16x16x32_bf16 v[90:93], v[144:147], v[184:187], v[90:93]
	v_mfma_f32_16x16x32_bf16 v[78:81], v[136:139], v[192:195], v[78:81]
	v_mfma_f32_16x16x32_bf16 v[74:77], v[144:147], v[192:195], v[74:77]
	v_mfma_f32_16x16x32_bf16 v[126:129], v[140:143], v[172:175], v[126:129]
	v_mfma_f32_16x16x32_bf16 v[122:125], v[148:151], v[172:175], v[122:125]
	v_mfma_f32_16x16x32_bf16 v[110:113], v[140:143], v[180:183], v[110:113]
	v_mfma_f32_16x16x32_bf16 v[106:109], v[148:151], v[180:183], v[106:109]
	v_mfma_f32_16x16x32_bf16 v[94:97], v[140:143], v[188:191], v[94:97]
	v_mfma_f32_16x16x32_bf16 v[90:93], v[148:151], v[188:191], v[90:93]
	v_mfma_f32_16x16x32_bf16 v[78:81], v[140:143], v[196:199], v[78:81]
	v_mfma_f32_16x16x32_bf16 v[74:77], v[148:151], v[196:199], v[74:77]
	v_mfma_f32_16x16x32_bf16 v[118:121], v[224:227], v[168:171], v[118:121]
	v_mfma_f32_16x16x32_bf16 v[114:117], v[232:235], v[168:171], v[114:117]
	v_mfma_f32_16x16x32_bf16 v[102:105], v[224:227], v[176:179], v[102:105]
	v_mfma_f32_16x16x32_bf16 v[98:101], v[232:235], v[176:179], v[98:101]
	v_mfma_f32_16x16x32_bf16 v[86:89], v[224:227], v[184:187], v[86:89]
	v_mfma_f32_16x16x32_bf16 v[82:85], v[232:235], v[184:187], v[82:85]
	v_mfma_f32_16x16x32_bf16 v[70:73], v[224:227], v[192:195], v[70:73]
	v_mfma_f32_16x16x32_bf16 v[66:69], v[232:235], v[192:195], v[66:69]
	v_mfma_f32_16x16x32_bf16 v[118:121], v[228:231], v[172:175], v[118:121]
	v_mfma_f32_16x16x32_bf16 v[114:117], v[236:239], v[172:175], v[114:117]
	v_mfma_f32_16x16x32_bf16 v[102:105], v[228:231], v[180:183], v[102:105]
	v_mfma_f32_16x16x32_bf16 v[98:101], v[236:239], v[180:183], v[98:101]
	v_mfma_f32_16x16x32_bf16 v[86:89], v[228:231], v[188:191], v[86:89]
	v_mfma_f32_16x16x32_bf16 v[82:85], v[236:239], v[188:191], v[82:85]
	v_mfma_f32_16x16x32_bf16 v[70:73], v[228:231], v[196:199], v[70:73]
	v_mfma_f32_16x16x32_bf16 v[66:69], v[236:239], v[196:199], v[66:69]
	s_barrier
	s_mov_b32 m0, s59
	ds_read_b128 v[168:171], v155 offset:49152
	ds_read_b128 v[172:175], v155 offset:50176
	ds_read_b128 v[176:179], v155 offset:51200
	ds_read_b128 v[180:183], v155 offset:52224
	ds_read_b128 v[184:187], v155 offset:53248
	ds_read_b128 v[188:191], v155 offset:54272
	ds_read_b128 v[192:195], v155 offset:55296
	ds_read_b128 v[196:199], v155 offset:56320
	global_load_lds_dwordx4 v0, s[78:79]
	s_mov_b32 m0, s60
	s_nop 0
	global_load_lds_dwordx4 v130, s[78:79]
	s_mov_b32 m0, s53
	s_nop 0
	global_load_lds_dwordx4 v0, s[76:77]
	s_add_i32 m0, s53, 0x2000
	s_add_u32 s50, s50, 0x80080
	s_addc_u32 s51, s51, 0
	global_load_lds_dwordx4 v130, s[76:77]
	s_add_i32 s52, s52, s54
	s_mov_b32 m0, s52
	s_nop 0
	global_load_lds_dwordx4 v0, s[50:51]
	s_add_i32 m0, s52, 0x2000
	s_nop 0
	global_load_lds_dwordx4 v130, s[50:51]
	s_waitcnt vmcnt(8) lgkmcnt(0)
	s_nop 0
	s_barrier
	v_mfma_f32_16x16x32_bf16 v[62:65], v[136:139], v[168:171], v[62:65]
	v_mfma_f32_16x16x32_bf16 v[58:61], v[144:147], v[168:171], v[58:61]
	v_mfma_f32_16x16x32_bf16 v[46:49], v[136:139], v[176:179], v[46:49]
	v_mfma_f32_16x16x32_bf16 v[42:45], v[144:147], v[176:179], v[42:45]
	v_mfma_f32_16x16x32_bf16 v[30:33], v[136:139], v[184:187], v[30:33]
	v_mfma_f32_16x16x32_bf16 v[26:29], v[144:147], v[184:187], v[26:29]
	v_mfma_f32_16x16x32_bf16 v[14:17], v[136:139], v[192:195], v[14:17]
	v_mfma_f32_16x16x32_bf16 v[10:13], v[144:147], v[192:195], v[10:13]
	v_mfma_f32_16x16x32_bf16 v[62:65], v[140:143], v[172:175], v[62:65]
	v_mfma_f32_16x16x32_bf16 v[58:61], v[148:151], v[172:175], v[58:61]
	v_mfma_f32_16x16x32_bf16 v[46:49], v[140:143], v[180:183], v[46:49]
	v_mfma_f32_16x16x32_bf16 v[42:45], v[148:151], v[180:183], v[42:45]
	v_mfma_f32_16x16x32_bf16 v[30:33], v[140:143], v[188:191], v[30:33]
	v_mfma_f32_16x16x32_bf16 v[26:29], v[148:151], v[188:191], v[26:29]
	v_mfma_f32_16x16x32_bf16 v[14:17], v[140:143], v[196:199], v[14:17]
	v_mfma_f32_16x16x32_bf16 v[10:13], v[148:151], v[196:199], v[10:13]
	v_mfma_f32_16x16x32_bf16 v[54:57], v[224:227], v[168:171], v[54:57]
	v_mfma_f32_16x16x32_bf16 v[50:53], v[232:235], v[168:171], v[50:53]
	v_mfma_f32_16x16x32_bf16 v[38:41], v[224:227], v[176:179], v[38:41]
	v_mfma_f32_16x16x32_bf16 v[34:37], v[232:235], v[176:179], v[34:37]
	v_mfma_f32_16x16x32_bf16 v[22:25], v[224:227], v[184:187], v[22:25]
	v_mfma_f32_16x16x32_bf16 v[18:21], v[232:235], v[184:187], v[18:21]
	v_mfma_f32_16x16x32_bf16 v[6:9], v[224:227], v[192:195], v[6:9]
	v_mfma_f32_16x16x32_bf16 v[2:5], v[232:235], v[192:195], v[2:5]
	v_mfma_f32_16x16x32_bf16 v[54:57], v[228:231], v[172:175], v[54:57]
	v_mfma_f32_16x16x32_bf16 v[50:53], v[236:239], v[172:175], v[50:53]
	v_mfma_f32_16x16x32_bf16 v[38:41], v[228:231], v[180:183], v[38:41]
	v_mfma_f32_16x16x32_bf16 v[34:37], v[236:239], v[180:183], v[34:37]
	v_mfma_f32_16x16x32_bf16 v[22:25], v[228:231], v[188:191], v[22:25]
	v_mfma_f32_16x16x32_bf16 v[18:21], v[236:239], v[188:191], v[18:21]
	v_mfma_f32_16x16x32_bf16 v[6:9], v[228:231], v[196:199], v[6:9]
	v_mfma_f32_16x16x32_bf16 v[2:5], v[236:239], v[196:199], v[2:5]
	s_barrier
	s_add_u32 s0, s0, 0x100
	s_addc_u32 s1, s1, 0
	s_add_u32 s13, s13, 0x100
	s_addc_u32 s66, s66, 0
	s_mov_b32 s50, s67
	s_cmp_ge_i32 s67, s41
	s_cbranch_scc0 .LBB0_282
	s_cmp_eq_u32 s63, 2
	s_cbranch_scc1 .Lepi6_orig
	v_readlane_b32 s90, v255, 17
	v_readlane_b32 s91, v255, 18
	v_readlane_b32 s96, v255, 19
	v_readlane_b32 s97, v255, 20
	v_readlane_b32 s8, v255, 25
	v_readlane_b32 s9, v255, 26
	v_readlane_b32 s68, v253, 58
	v_readlane_b32 s69, v253, 59
	v_lshl_or_b32 v156, s64, 8, v154
	v_lshlrev_b32_e32 v156, 2, v156
	v_lshl_add_u32 v157, v152, 13, v156
	s_lshl_b32 s72, s65, 21
	s_add_u32 s74, s68, s72
	s_addc_u32 s75, s69, 0
	s_add_u32 s76, s22, s72
	s_addc_u32 s77, s23, 0
	s_lshr_b32 s73, s65, 3
	s_mul_i32 s73, s73, 0xc000
	s_add_u32 s73, s73, 0x4000
	s_add_u32 s70, s90, s73
	s_addc_u32 s71, s91, 0
	global_load_dwordx4 v[140:143], v156, s[70:71]
	global_load_dwordx4 v[144:147], v156, s[70:71] offset:64
	global_load_dwordx4 v[148:151], v156, s[70:71] offset:512
	global_load_dwordx4 v[168:171], v156, s[70:71] offset:576
	global_load_dwordx4 v[224:227], v157, s[74:75] nt
	global_load_dwordx4 v[228:231], v157, s[74:75] offset:64 nt
	global_load_dwordx4 v[232:235], v157, s[74:75] offset:512 nt
	global_load_dwordx4 v[236:239], v157, s[74:75] offset:576 nt
	s_add_u32 s74, s74, 0x20000
	s_addc_u32 s75, s75, 0
	global_load_dwordx4 v[240:243], v157, s[74:75] nt
	global_load_dwordx4 v[244:247], v157, s[74:75] offset:64 nt
	s_waitcnt vmcnt(5)
	v_pk_fma_f32 v[128:129], v[128:129], v[142:143], v[226:227]
	v_pk_fma_f32 v[126:127], v[126:127], v[140:141], v[224:225]
	global_store_dwordx4 v157, v[126:129], s[76:77]
	global_load_dwordx4 v[224:227], v157, s[74:75] offset:512 nt
	s_waitcnt vmcnt(6)
	v_pk_fma_f32 v[124:125], v[124:125], v[146:147], v[230:231]
	v_pk_fma_f32 v[122:123], v[122:123], v[144:145], v[228:229]
	global_store_dwordx4 v157, v[122:125], s[76:77] offset:64
	global_load_dwordx4 v[228:231], v157, s[74:75] offset:576 nt
	s_waitcnt vmcnt(7)
	v_pk_fma_f32 v[120:121], v[120:121], v[150:151], v[234:235]
	v_pk_fma_f32 v[118:119], v[118:119], v[148:149], v[232:233]
	global_store_dwordx4 v157, v[118:121], s[76:77] offset:512
	s_add_u32 s74, s74, 0x20000
	s_addc_u32 s75, s75, 0
	global_load_dwordx4 v[232:235], v157, s[74:75] nt
	s_waitcnt vmcnt(8)
	v_pk_fma_f32 v[116:117], v[116:117], v[170:171], v[238:239]
	v_pk_fma_f32 v[114:115], v[114:115], v[168:169], v[236:237]
	global_store_dwordx4 v157, v[114:117], s[76:77] offset:576
	global_load_dwordx4 v[236:239], v157, s[74:75] offset:64 nt
	s_add_u32 s76, s76, 0x20000
	s_addc_u32 s77, s77, 0
	s_waitcnt vmcnt(9)
	v_pk_fma_f32 v[112:113], v[112:113], v[142:143], v[242:243]
	v_pk_fma_f32 v[110:111], v[110:111], v[140:141], v[240:241]
	global_store_dwordx4 v157, v[110:113], s[76:77]
	global_load_dwordx4 v[240:243], v157, s[74:75] offset:512 nt
	s_waitcnt vmcnt(10)
	v_pk_fma_f32 v[108:109], v[108:109], v[146:147], v[246:247]
	v_pk_fma_f32 v[106:107], v[106:107], v[144:145], v[244:245]
	global_store_dwordx4 v157, v[106:109], s[76:77] offset:64
	global_load_dwordx4 v[244:247], v157, s[74:75] offset:576 nt
	s_waitcnt vmcnt(10)
	v_pk_fma_f32 v[104:105], v[104:105], v[150:151], v[226:227]
	v_pk_fma_f32 v[102:103], v[102:103], v[148:149], v[224:225]
	global_store_dwordx4 v157, v[102:105], s[76:77] offset:512
	s_add_u32 s74, s74, 0x20000
	s_addc_u32 s75, s75, 0
	global_load_dwordx4 v[224:227], v157, s[74:75] nt
	s_waitcnt vmcnt(10)
	v_pk_fma_f32 v[100:101], v[100:101], v[170:171], v[230:231]
	v_pk_fma_f32 v[98:99], v[98:99], v[168:169], v[228:229]
	global_store_dwordx4 v157, v[98:101], s[76:77] offset:576
	global_load_dwordx4 v[228:231], v157, s[74:75] offset:64 nt
	s_add_u32 s76, s76, 0x20000
	s_addc_u32 s77, s77, 0
	s_waitcnt vmcnt(10)
	v_pk_fma_f32 v[96:97], v[96:97], v[142:143], v[234:235]
	v_pk_fma_f32 v[94:95], v[94:95], v[140:141], v[232:233]
	global_store_dwordx4 v157, v[94:97], s[76:77]
	global_load_dwordx4 v[232:235], v157, s[74:75] offset:512 nt
	s_waitcnt vmcnt(10)
	v_pk_fma_f32 v[92:93], v[92:93], v[146:147], v[238:239]
	v_pk_fma_f32 v[90:91], v[90:91], v[144:145], v[236:237]
	global_store_dwordx4 v157, v[90:93], s[76:77] offset:64
	global_load_dwordx4 v[236:239], v157, s[74:75] offset:576 nt
	s_waitcnt vmcnt(10)
	v_pk_fma_f32 v[88:89], v[88:89], v[150:151], v[242:243]
	v_pk_fma_f32 v[86:87], v[86:87], v[148:149], v[240:241]
	global_store_dwordx4 v157, v[86:89], s[76:77] offset:512
	s_add_u32 s74, s74, 0xa0000
	s_addc_u32 s75, s75, 0
	global_load_dwordx4 v[240:243], v157, s[74:75] nt
	s_waitcnt vmcnt(10)
	v_pk_fma_f32 v[84:85], v[84:85], v[170:171], v[246:247]
	v_pk_fma_f32 v[82:83], v[82:83], v[168:169], v[244:245]
	global_store_dwordx4 v157, v[82:85], s[76:77] offset:576
	global_load_dwordx4 v[244:247], v157, s[74:75] offset:64 nt
	s_add_u32 s76, s76, 0x20000
	s_addc_u32 s77, s77, 0
	s_waitcnt vmcnt(10)
	v_pk_fma_f32 v[80:81], v[80:81], v[142:143], v[226:227]
	v_pk_fma_f32 v[78:79], v[78:79], v[140:141], v[224:225]
	global_store_dwordx4 v157, v[78:81], s[76:77]
	global_load_dwordx4 v[224:227], v157, s[74:75] offset:512 nt
	s_waitcnt vmcnt(10)
	v_pk_fma_f32 v[76:77], v[76:77], v[146:147], v[230:231]
	v_pk_fma_f32 v[74:75], v[74:75], v[144:145], v[228:229]
	global_store_dwordx4 v157, v[74:77], s[76:77] offset:64
	global_load_dwordx4 v[228:231], v157, s[74:75] offset:576 nt
	s_waitcnt vmcnt(10)
	v_pk_fma_f32 v[72:73], v[72:73], v[150:151], v[234:235]
	v_pk_fma_f32 v[70:71], v[70:71], v[148:149], v[232:233]
	global_store_dwordx4 v157, v[70:73], s[76:77] offset:512
	s_add_u32 s74, s74, 0x20000
	s_addc_u32 s75, s75, 0
	global_load_dwordx4 v[232:235], v157, s[74:75] nt
	s_waitcnt vmcnt(10)
	v_pk_fma_f32 v[68:69], v[68:69], v[170:171], v[238:239]
	v_pk_fma_f32 v[66:67], v[66:67], v[168:169], v[236:237]
	global_store_dwordx4 v157, v[66:69], s[76:77] offset:576
	global_load_dwordx4 v[236:239], v157, s[74:75] offset:64 nt
	s_add_u32 s76, s76, 0xa0000
	s_addc_u32 s77, s77, 0
	s_waitcnt vmcnt(10)
	v_pk_fma_f32 v[64:65], v[64:65], v[142:143], v[242:243]
	v_pk_fma_f32 v[62:63], v[62:63], v[140:141], v[240:241]
	global_store_dwordx4 v157, v[62:65], s[76:77]
	global_load_dwordx4 v[240:243], v157, s[74:75] offset:512 nt
	s_waitcnt vmcnt(10)
	v_pk_fma_f32 v[60:61], v[60:61], v[146:147], v[246:247]
	v_pk_fma_f32 v[58:59], v[58:59], v[144:145], v[244:245]
	global_store_dwordx4 v157, v[58:61], s[76:77] offset:64
	global_load_dwordx4 v[244:247], v157, s[74:75] offset:576 nt
	s_waitcnt vmcnt(10)
	v_pk_fma_f32 v[56:57], v[56:57], v[150:151], v[226:227]
	v_pk_fma_f32 v[54:55], v[54:55], v[148:149], v[224:225]
	global_store_dwordx4 v157, v[54:57], s[76:77] offset:512
	s_add_u32 s74, s74, 0x20000
	s_addc_u32 s75, s75, 0
	global_load_dwordx4 v[224:227], v157, s[74:75] nt
	s_waitcnt vmcnt(10)
	v_pk_fma_f32 v[52:53], v[52:53], v[170:171], v[230:231]
	v_pk_fma_f32 v[50:51], v[50:51], v[168:169], v[228:229]
	global_store_dwordx4 v157, v[50:53], s[76:77] offset:576
	global_load_dwordx4 v[228:231], v157, s[74:75] offset:64 nt
	s_add_u32 s76, s76, 0x20000
	s_addc_u32 s77, s77, 0
	s_waitcnt vmcnt(10)
	v_pk_fma_f32 v[48:49], v[48:49], v[142:143], v[234:235]
	v_pk_fma_f32 v[46:47], v[46:47], v[140:141], v[232:233]
	global_store_dwordx4 v157, v[46:49], s[76:77]
	global_load_dwordx4 v[232:235], v157, s[74:75] offset:512 nt
	s_waitcnt vmcnt(10)
	v_pk_fma_f32 v[44:45], v[44:45], v[146:147], v[238:239]
	v_pk_fma_f32 v[42:43], v[42:43], v[144:145], v[236:237]
	global_store_dwordx4 v157, v[42:45], s[76:77] offset:64
	global_load_dwordx4 v[236:239], v157, s[74:75] offset:576 nt
	s_waitcnt vmcnt(10)
	v_pk_fma_f32 v[40:41], v[40:41], v[150:151], v[242:243]
	v_pk_fma_f32 v[38:39], v[38:39], v[148:149], v[240:241]
	global_store_dwordx4 v157, v[38:41], s[76:77] offset:512
	s_add_u32 s74, s74, 0x20000
	s_addc_u32 s75, s75, 0
	global_load_dwordx4 v[240:243], v157, s[74:75] nt
	s_waitcnt vmcnt(10)
	v_pk_fma_f32 v[36:37], v[36:37], v[170:171], v[246:247]
	v_pk_fma_f32 v[34:35], v[34:35], v[168:169], v[244:245]
	global_store_dwordx4 v157, v[34:37], s[76:77] offset:576
	global_load_dwordx4 v[244:247], v157, s[74:75] offset:64 nt
	s_add_u32 s76, s76, 0x20000
	s_addc_u32 s77, s77, 0
	s_waitcnt vmcnt(10)
	v_pk_fma_f32 v[32:33], v[32:33], v[142:143], v[226:227]
	v_pk_fma_f32 v[30:31], v[30:31], v[140:141], v[224:225]
	global_store_dwordx4 v157, v[30:33], s[76:77]
	global_load_dwordx4 v[224:227], v157, s[74:75] offset:512 nt
	s_waitcnt vmcnt(10)
	v_pk_fma_f32 v[28:29], v[28:29], v[146:147], v[230:231]
	v_pk_fma_f32 v[26:27], v[26:27], v[144:145], v[228:229]
	global_store_dwordx4 v157, v[26:29], s[76:77] offset:64
	global_load_dwordx4 v[228:231], v157, s[74:75] offset:576 nt
	s_waitcnt vmcnt(10)
	v_pk_fma_f32 v[24:25], v[24:25], v[150:151], v[234:235]
	v_pk_fma_f32 v[22:23], v[22:23], v[148:149], v[232:233]
	global_store_dwordx4 v157, v[22:25], s[76:77] offset:512
	s_waitcnt vmcnt(9)
	v_pk_fma_f32 v[20:21], v[20:21], v[170:171], v[238:239]
	v_pk_fma_f32 v[18:19], v[18:19], v[168:169], v[236:237]
	global_store_dwordx4 v157, v[18:21], s[76:77] offset:576
	s_add_u32 s76, s76, 0x20000
	s_addc_u32 s77, s77, 0
	s_waitcnt vmcnt(8)
	v_pk_fma_f32 v[16:17], v[16:17], v[142:143], v[242:243]
	v_pk_fma_f32 v[14:15], v[14:15], v[140:141], v[240:241]
	global_store_dwordx4 v157, v[14:17], s[76:77]
	s_waitcnt vmcnt(7)
	v_pk_fma_f32 v[12:13], v[12:13], v[146:147], v[246:247]
	v_pk_fma_f32 v[10:11], v[10:11], v[144:145], v[244:245]
	global_store_dwordx4 v157, v[10:13], s[76:77] offset:64
	s_waitcnt vmcnt(6)
	v_pk_fma_f32 v[8:9], v[8:9], v[150:151], v[226:227]
	v_pk_fma_f32 v[6:7], v[6:7], v[148:149], v[224:225]
	global_store_dwordx4 v157, v[6:9], s[76:77] offset:512
	s_waitcnt vmcnt(5)
	v_pk_fma_f32 v[4:5], v[4:5], v[170:171], v[230:231]
	v_pk_fma_f32 v[2:3], v[2:3], v[168:169], v[228:229]
	global_store_dwordx4 v157, v[2:5], s[76:77] offset:576
	s_branch .LBB0_269

.LBB0_572:
	s_add_u32 s41, s46, 0xfff80080
	s_addc_u32 s48, s47, -1
	s_add_i32 s64, 0, 0x10000
	ds_read_b128 v[144:147], v141
	ds_read_b128 v[148:151], v141 offset:1024
	ds_read_b128 v[152:155], v141 offset:2048
	ds_read_b128 v[168:171], v141 offset:3072
	s_cmp_eq_u32 s39, 28
	s_cselect_b32 s51, s43, s48
	s_cselect_b32 s50, s42, s41
	s_cselect_b32 s49, s45, s13
	s_cselect_b32 s48, s44, s12
	ds_read_b128 v[172:175], v143
	ds_read_b128 v[176:179], v143 offset:1024
	ds_read_b128 v[180:183], v143 offset:2048
	ds_read_b128 v[184:187], v143 offset:3072
	ds_read_b128 v[188:191], v143 offset:4096
	ds_read_b128 v[192:195], v143 offset:5120
	ds_read_b128 v[196:199], v143 offset:6144
	ds_read_b128 v[224:227], v143 offset:7168
	s_add_i32 m0, s54, 0xc000
	s_nop 0
	global_load_lds_dwordx4 v136, s[46:47]
	s_add_i32 m0, s54, 0xe000
	s_add_i32 s41, 0, 0x14000
	global_load_lds_dwordx4 v138, s[46:47]
	s_add_i32 s64, s64, s53
	ds_read_b128 v[228:231], v141 offset:16384
	ds_read_b128 v[232:235], v141 offset:17408
	ds_read_b128 v[236:239], v141 offset:18432
	ds_read_b128 v[240:243], v141 offset:19456
	s_waitcnt vmcnt(8) lgkmcnt(0)
	s_barrier
	v_mfma_f32_16x16x32_bf16 v[126:129], v[144:147], v[172:175], v[126:129]
	v_mfma_f32_16x16x32_bf16 v[122:125], v[152:155], v[172:175], v[122:125]
	v_mfma_f32_16x16x32_bf16 v[118:121], v[144:147], v[180:183], v[118:121]
	v_mfma_f32_16x16x32_bf16 v[114:117], v[152:155], v[180:183], v[114:117]
	v_mfma_f32_16x16x32_bf16 v[102:105], v[144:147], v[188:191], v[102:105]
	v_mfma_f32_16x16x32_bf16 v[98:101], v[152:155], v[188:191], v[98:101]
	v_mfma_f32_16x16x32_bf16 v[86:89], v[144:147], v[196:199], v[86:89]
	v_mfma_f32_16x16x32_bf16 v[82:85], v[152:155], v[196:199], v[82:85]
	v_mfma_f32_16x16x32_bf16 v[126:129], v[148:151], v[176:179], v[126:129]
	v_mfma_f32_16x16x32_bf16 v[122:125], v[168:171], v[176:179], v[122:125]
	v_mfma_f32_16x16x32_bf16 v[118:121], v[148:151], v[184:187], v[118:121]
	v_mfma_f32_16x16x32_bf16 v[114:117], v[168:171], v[184:187], v[114:117]
	v_mfma_f32_16x16x32_bf16 v[102:105], v[148:151], v[192:195], v[102:105]
	v_mfma_f32_16x16x32_bf16 v[98:101], v[168:171], v[192:195], v[98:101]
	v_mfma_f32_16x16x32_bf16 v[86:89], v[148:151], v[224:227], v[86:89]
	v_mfma_f32_16x16x32_bf16 v[82:85], v[168:171], v[224:227], v[82:85]
	v_mfma_f32_16x16x32_bf16 v[110:113], v[228:231], v[172:175], v[110:113]
	v_mfma_f32_16x16x32_bf16 v[106:109], v[236:239], v[172:175], v[106:109]
	v_mfma_f32_16x16x32_bf16 v[94:97], v[228:231], v[180:183], v[94:97]
	v_mfma_f32_16x16x32_bf16 v[90:93], v[236:239], v[180:183], v[90:93]
	v_mfma_f32_16x16x32_bf16 v[78:81], v[228:231], v[188:191], v[78:81]
	v_mfma_f32_16x16x32_bf16 v[74:77], v[236:239], v[188:191], v[74:77]
	v_mfma_f32_16x16x32_bf16 v[70:73], v[228:231], v[196:199], v[70:73]
	v_mfma_f32_16x16x32_bf16 v[66:69], v[236:239], v[196:199], v[66:69]
	v_mfma_f32_16x16x32_bf16 v[110:113], v[232:235], v[176:179], v[110:113]
	v_mfma_f32_16x16x32_bf16 v[106:109], v[240:243], v[176:179], v[106:109]
	v_mfma_f32_16x16x32_bf16 v[94:97], v[232:235], v[184:187], v[94:97]
	v_mfma_f32_16x16x32_bf16 v[90:93], v[240:243], v[184:187], v[90:93]
	v_mfma_f32_16x16x32_bf16 v[78:81], v[232:235], v[192:195], v[78:81]
	v_mfma_f32_16x16x32_bf16 v[74:77], v[240:243], v[192:195], v[74:77]
	v_mfma_f32_16x16x32_bf16 v[70:73], v[232:235], v[224:227], v[70:73]
	v_mfma_f32_16x16x32_bf16 v[66:69], v[240:243], v[224:227], v[66:69]
	s_barrier
	s_mov_b32 m0, s54
	s_add_u32 s78, s50, s94
	s_addc_u32 s79, s51, s95
	ds_read_b128 v[172:175], v143 offset:16384
	ds_read_b128 v[176:179], v143 offset:17408
	ds_read_b128 v[180:183], v143 offset:18432
	ds_read_b128 v[184:187], v143 offset:19456
	ds_read_b128 v[188:191], v143 offset:20480
	ds_read_b128 v[192:195], v143 offset:21504
	ds_read_b128 v[196:199], v143 offset:22528
	ds_read_b128 v[224:227], v143 offset:23552
	global_load_lds_dwordx4 v130, s[50:51]
	s_mov_b32 m0, s55
	s_add_u32 s76, s48, s94
	s_addc_u32 s77, s49, s95
	global_load_lds_dwordx4 v132, s[50:51]
	s_mov_b32 m0, s64
	s_nop 0
	global_load_lds_dwordx4 v0, s[48:49]
	s_add_i32 m0, s64, 0x2000
	s_add_u32 s64, s48, 0x80000
	s_addc_u32 s65, s49, 0
	global_load_lds_dwordx4 v134, s[48:49]
	s_add_i32 s41, s41, s53
	s_mov_b32 m0, s41
	s_nop 0
	global_load_lds_dwordx4 v0, s[64:65]
	s_add_i32 m0, s41, 0x2000
	s_nop 0
	global_load_lds_dwordx4 v134, s[64:65]
	s_waitcnt vmcnt(8) lgkmcnt(0)
	s_barrier
	v_mfma_f32_16x16x32_bf16 v[62:65], v[144:147], v[172:175], v[62:65]
	v_mfma_f32_16x16x32_bf16 v[58:61], v[152:155], v[172:175], v[58:61]
	v_mfma_f32_16x16x32_bf16 v[54:57], v[144:147], v[180:183], v[54:57]
	v_mfma_f32_16x16x32_bf16 v[50:53], v[152:155], v[180:183], v[50:53]
	v_mfma_f32_16x16x32_bf16 v[38:41], v[144:147], v[188:191], v[38:41]
	v_mfma_f32_16x16x32_bf16 v[34:37], v[152:155], v[188:191], v[34:37]
	v_mfma_f32_16x16x32_bf16 v[22:25], v[144:147], v[196:199], v[22:25]
	v_mfma_f32_16x16x32_bf16 v[18:21], v[152:155], v[196:199], v[18:21]
	v_mfma_f32_16x16x32_bf16 v[62:65], v[148:151], v[176:179], v[62:65]
	v_mfma_f32_16x16x32_bf16 v[58:61], v[168:171], v[176:179], v[58:61]
	v_mfma_f32_16x16x32_bf16 v[54:57], v[148:151], v[184:187], v[54:57]
	v_mfma_f32_16x16x32_bf16 v[50:53], v[168:171], v[184:187], v[50:53]
	v_mfma_f32_16x16x32_bf16 v[38:41], v[148:151], v[192:195], v[38:41]
	v_mfma_f32_16x16x32_bf16 v[34:37], v[168:171], v[192:195], v[34:37]
	v_mfma_f32_16x16x32_bf16 v[22:25], v[148:151], v[224:227], v[22:25]
	v_mfma_f32_16x16x32_bf16 v[18:21], v[168:171], v[224:227], v[18:21]
	v_mfma_f32_16x16x32_bf16 v[46:49], v[228:231], v[172:175], v[46:49]
	v_mfma_f32_16x16x32_bf16 v[42:45], v[236:239], v[172:175], v[42:45]
	v_mfma_f32_16x16x32_bf16 v[30:33], v[228:231], v[180:183], v[30:33]
	v_mfma_f32_16x16x32_bf16 v[26:29], v[236:239], v[180:183], v[26:29]
	v_mfma_f32_16x16x32_bf16 v[14:17], v[228:231], v[188:191], v[14:17]
	v_mfma_f32_16x16x32_bf16 v[10:13], v[236:239], v[188:191], v[10:13]
	v_mfma_f32_16x16x32_bf16 v[6:9], v[228:231], v[196:199], v[6:9]
	v_mfma_f32_16x16x32_bf16 v[2:5], v[236:239], v[196:199], v[2:5]
	v_mfma_f32_16x16x32_bf16 v[46:49], v[232:235], v[176:179], v[46:49]
	v_mfma_f32_16x16x32_bf16 v[42:45], v[240:243], v[176:179], v[42:45]
	v_mfma_f32_16x16x32_bf16 v[30:33], v[232:235], v[184:187], v[30:33]
	v_mfma_f32_16x16x32_bf16 v[26:29], v[240:243], v[184:187], v[26:29]
	v_mfma_f32_16x16x32_bf16 v[14:17], v[232:235], v[192:195], v[14:17]
	v_mfma_f32_16x16x32_bf16 v[10:13], v[240:243], v[192:195], v[10:13]
	v_mfma_f32_16x16x32_bf16 v[6:9], v[232:235], v[224:227], v[6:9]
	v_mfma_f32_16x16x32_bf16 v[2:5], v[240:243], v[224:227], v[2:5]
	s_barrier
	s_add_i32 s41, 0, 0x18000
	ds_read_b128 v[144:147], v141 offset:32768
	ds_read_b128 v[148:151], v141 offset:33792
	ds_read_b128 v[152:155], v141 offset:34816
	ds_read_b128 v[168:171], v141 offset:35840
	s_add_u32 s50, s50, 0x80000
	s_addc_u32 s51, s51, 0
	ds_read_b128 v[172:175], v143 offset:32768
	ds_read_b128 v[176:179], v143 offset:33792
	ds_read_b128 v[180:183], v143 offset:34816
	ds_read_b128 v[184:187], v143 offset:35840
	ds_read_b128 v[188:191], v143 offset:36864
	ds_read_b128 v[192:195], v143 offset:37888
	ds_read_b128 v[196:199], v143 offset:38912
	ds_read_b128 v[224:227], v143 offset:39936
	s_mov_b32 m0, s56
	s_nop 0
	global_load_lds_dwordx4 v130, s[50:51]
	s_mov_b32 m0, s57
	s_nop 0
	global_load_lds_dwordx4 v132, s[50:51]
	s_add_i32 s50, 0, 0x1c000
	s_add_i32 s41, s41, s53
	ds_read_b128 v[228:231], v141 offset:49152
	ds_read_b128 v[232:235], v141 offset:50176
	ds_read_b128 v[236:239], v141 offset:51200
	ds_read_b128 v[240:243], v141 offset:52224
	s_waitcnt vmcnt(8) lgkmcnt(0)
	s_nop 0
	s_barrier
	v_mfma_f32_16x16x32_bf16 v[126:129], v[144:147], v[172:175], v[126:129]
	v_mfma_f32_16x16x32_bf16 v[122:125], v[152:155], v[172:175], v[122:125]
	v_mfma_f32_16x16x32_bf16 v[118:121], v[144:147], v[180:183], v[118:121]
	v_mfma_f32_16x16x32_bf16 v[114:117], v[152:155], v[180:183], v[114:117]
	v_mfma_f32_16x16x32_bf16 v[102:105], v[144:147], v[188:191], v[102:105]
	v_mfma_f32_16x16x32_bf16 v[98:101], v[152:155], v[188:191], v[98:101]
	v_mfma_f32_16x16x32_bf16 v[86:89], v[144:147], v[196:199], v[86:89]
	v_mfma_f32_16x16x32_bf16 v[82:85], v[152:155], v[196:199], v[82:85]
	v_mfma_f32_16x16x32_bf16 v[126:129], v[148:151], v[176:179], v[126:129]
	v_mfma_f32_16x16x32_bf16 v[122:125], v[168:171], v[176:179], v[122:125]
	v_mfma_f32_16x16x32_bf16 v[118:121], v[148:151], v[184:187], v[118:121]
	v_mfma_f32_16x16x32_bf16 v[114:117], v[168:171], v[184:187], v[114:117]
	v_mfma_f32_16x16x32_bf16 v[102:105], v[148:151], v[192:195], v[102:105]
	v_mfma_f32_16x16x32_bf16 v[98:101], v[168:171], v[192:195], v[98:101]
	v_mfma_f32_16x16x32_bf16 v[86:89], v[148:151], v[224:227], v[86:89]
	v_mfma_f32_16x16x32_bf16 v[82:85], v[168:171], v[224:227], v[82:85]
	v_mfma_f32_16x16x32_bf16 v[110:113], v[228:231], v[172:175], v[110:113]
	v_mfma_f32_16x16x32_bf16 v[106:109], v[236:239], v[172:175], v[106:109]
	v_mfma_f32_16x16x32_bf16 v[94:97], v[228:231], v[180:183], v[94:97]
	v_mfma_f32_16x16x32_bf16 v[90:93], v[236:239], v[180:183], v[90:93]
	v_mfma_f32_16x16x32_bf16 v[78:81], v[228:231], v[188:191], v[78:81]
	v_mfma_f32_16x16x32_bf16 v[74:77], v[236:239], v[188:191], v[74:77]
	v_mfma_f32_16x16x32_bf16 v[70:73], v[228:231], v[196:199], v[70:73]
	v_mfma_f32_16x16x32_bf16 v[66:69], v[236:239], v[196:199], v[66:69]
	v_mfma_f32_16x16x32_bf16 v[110:113], v[232:235], v[176:179], v[110:113]
	v_mfma_f32_16x16x32_bf16 v[106:109], v[240:243], v[176:179], v[106:109]
	v_mfma_f32_16x16x32_bf16 v[94:97], v[232:235], v[184:187], v[94:97]
	v_mfma_f32_16x16x32_bf16 v[90:93], v[240:243], v[184:187], v[90:93]
	v_mfma_f32_16x16x32_bf16 v[78:81], v[232:235], v[192:195], v[78:81]
	v_mfma_f32_16x16x32_bf16 v[74:77], v[240:243], v[192:195], v[74:77]
	v_mfma_f32_16x16x32_bf16 v[70:73], v[232:235], v[224:227], v[70:73]
	v_mfma_f32_16x16x32_bf16 v[66:69], v[240:243], v[224:227], v[66:69]
	s_barrier
	s_mov_b32 m0, s59
	ds_read_b128 v[172:175], v143 offset:49152
	ds_read_b128 v[176:179], v143 offset:50176
	ds_read_b128 v[180:183], v143 offset:51200
	ds_read_b128 v[184:187], v143 offset:52224
	ds_read_b128 v[188:191], v143 offset:53248
	ds_read_b128 v[192:195], v143 offset:54272
	ds_read_b128 v[196:199], v143 offset:55296
	ds_read_b128 v[224:227], v143 offset:56320
	global_load_lds_dwordx4 v130, s[78:79]
	s_mov_b32 m0, s60
	s_nop 0
	global_load_lds_dwordx4 v132, s[78:79]
	s_mov_b32 m0, s41
	s_nop 0
	global_load_lds_dwordx4 v0, s[76:77]
	s_add_i32 m0, s41, 0x2000
	s_add_u32 s48, s48, 0x80080
	s_addc_u32 s49, s49, 0
	global_load_lds_dwordx4 v134, s[76:77]
	s_add_i32 s41, s50, s53
	s_mov_b32 m0, s41
	s_nop 0
	global_load_lds_dwordx4 v0, s[48:49]
	s_add_i32 m0, s41, 0x2000
	s_nop 0
	global_load_lds_dwordx4 v134, s[48:49]
	s_waitcnt vmcnt(8) lgkmcnt(0)
	s_nop 0
	s_barrier
	v_mfma_f32_16x16x32_bf16 v[62:65], v[144:147], v[172:175], v[62:65]
	v_mfma_f32_16x16x32_bf16 v[58:61], v[152:155], v[172:175], v[58:61]
	v_mfma_f32_16x16x32_bf16 v[54:57], v[144:147], v[180:183], v[54:57]
	v_mfma_f32_16x16x32_bf16 v[50:53], v[152:155], v[180:183], v[50:53]
	v_mfma_f32_16x16x32_bf16 v[38:41], v[144:147], v[188:191], v[38:41]
	v_mfma_f32_16x16x32_bf16 v[34:37], v[152:155], v[188:191], v[34:37]
	v_mfma_f32_16x16x32_bf16 v[22:25], v[144:147], v[196:199], v[22:25]
	v_mfma_f32_16x16x32_bf16 v[18:21], v[152:155], v[196:199], v[18:21]
	v_mfma_f32_16x16x32_bf16 v[62:65], v[148:151], v[176:179], v[62:65]
	v_mfma_f32_16x16x32_bf16 v[58:61], v[168:171], v[176:179], v[58:61]
	v_mfma_f32_16x16x32_bf16 v[54:57], v[148:151], v[184:187], v[54:57]
	v_mfma_f32_16x16x32_bf16 v[50:53], v[168:171], v[184:187], v[50:53]
	v_mfma_f32_16x16x32_bf16 v[38:41], v[148:151], v[192:195], v[38:41]
	v_mfma_f32_16x16x32_bf16 v[34:37], v[168:171], v[192:195], v[34:37]
	v_mfma_f32_16x16x32_bf16 v[22:25], v[148:151], v[224:227], v[22:25]
	v_mfma_f32_16x16x32_bf16 v[18:21], v[168:171], v[224:227], v[18:21]
	v_mfma_f32_16x16x32_bf16 v[46:49], v[228:231], v[172:175], v[46:49]
	v_mfma_f32_16x16x32_bf16 v[42:45], v[236:239], v[172:175], v[42:45]
	v_mfma_f32_16x16x32_bf16 v[30:33], v[228:231], v[180:183], v[30:33]
	v_mfma_f32_16x16x32_bf16 v[26:29], v[236:239], v[180:183], v[26:29]
	v_mfma_f32_16x16x32_bf16 v[14:17], v[228:231], v[188:191], v[14:17]
	v_mfma_f32_16x16x32_bf16 v[10:13], v[236:239], v[188:191], v[10:13]
	v_mfma_f32_16x16x32_bf16 v[6:9], v[228:231], v[196:199], v[6:9]
	v_mfma_f32_16x16x32_bf16 v[2:5], v[236:239], v[196:199], v[2:5]
	v_mfma_f32_16x16x32_bf16 v[46:49], v[232:235], v[176:179], v[46:49]
	v_mfma_f32_16x16x32_bf16 v[42:45], v[240:243], v[176:179], v[42:45]
	v_mfma_f32_16x16x32_bf16 v[30:33], v[232:235], v[184:187], v[30:33]
	v_mfma_f32_16x16x32_bf16 v[26:29], v[240:243], v[184:187], v[26:29]
	v_mfma_f32_16x16x32_bf16 v[14:17], v[232:235], v[192:195], v[14:17]
	v_mfma_f32_16x16x32_bf16 v[10:13], v[240:243], v[192:195], v[10:13]
	v_mfma_f32_16x16x32_bf16 v[6:9], v[232:235], v[224:227], v[6:9]
	v_mfma_f32_16x16x32_bf16 v[2:5], v[240:243], v[224:227], v[2:5]
	s_barrier
	s_add_i32 s39, s39, 2
	s_add_u32 s46, s46, 0x100
	s_addc_u32 s47, s47, 0
	s_add_u32 s12, s12, 0x100
	s_addc_u32 s13, s13, 0
	s_cmp_gt_u32 s39, 29
	s_cbranch_scc0 .LBB0_572
	s_cmp_lg_u32 s62, 0
	s_cbranch_scc0 .LBB0_575
	s_lshl_b32 s39, s61, 8
	s_mov_b64 s[12:13], 0
	s_branch .LBB0_576

.LBB0_788:
	s_add_u32 s39, s46, 0xfff80080
	s_addc_u32 s48, s47, -1
	s_add_i32 s64, 0, 0x10000
	ds_read_b128 v[144:147], v141
	ds_read_b128 v[148:151], v141 offset:1024
	ds_read_b128 v[152:155], v141 offset:2048
	ds_read_b128 v[168:171], v141 offset:3072
	s_cmp_eq_u32 s13, 28
	s_cselect_b32 s51, s43, s48
	s_cselect_b32 s50, s42, s39
	s_cselect_b32 s49, s45, s12
	s_cselect_b32 s48, s44, s1
	ds_read_b128 v[172:175], v143
	ds_read_b128 v[176:179], v143 offset:1024
	ds_read_b128 v[180:183], v143 offset:2048
	ds_read_b128 v[184:187], v143 offset:3072
	ds_read_b128 v[188:191], v143 offset:4096
	ds_read_b128 v[192:195], v143 offset:5120
	ds_read_b128 v[196:199], v143 offset:6144
	ds_read_b128 v[224:227], v143 offset:7168
	s_add_i32 m0, s54, 0xc000
	s_nop 0
	global_load_lds_dwordx4 v136, s[46:47]
	s_add_i32 m0, s54, 0xe000
	s_add_i32 s39, 0, 0x14000
	global_load_lds_dwordx4 v138, s[46:47]
	s_add_i32 s64, s64, s53
	ds_read_b128 v[228:231], v141 offset:16384
	ds_read_b128 v[232:235], v141 offset:17408
	ds_read_b128 v[236:239], v141 offset:18432
	ds_read_b128 v[240:243], v141 offset:19456
	s_waitcnt vmcnt(8) lgkmcnt(0)
	s_nop 0
	s_barrier
	v_mfma_f32_16x16x32_bf16 v[126:129], v[144:147], v[172:175], v[126:129]
	v_mfma_f32_16x16x32_bf16 v[122:125], v[152:155], v[172:175], v[122:125]
	v_mfma_f32_16x16x32_bf16 v[118:121], v[144:147], v[180:183], v[118:121]
	v_mfma_f32_16x16x32_bf16 v[114:117], v[152:155], v[180:183], v[114:117]
	v_mfma_f32_16x16x32_bf16 v[102:105], v[144:147], v[188:191], v[102:105]
	v_mfma_f32_16x16x32_bf16 v[98:101], v[152:155], v[188:191], v[98:101]
	v_mfma_f32_16x16x32_bf16 v[86:89], v[144:147], v[196:199], v[86:89]
	v_mfma_f32_16x16x32_bf16 v[82:85], v[152:155], v[196:199], v[82:85]
	v_mfma_f32_16x16x32_bf16 v[126:129], v[148:151], v[176:179], v[126:129]
	v_mfma_f32_16x16x32_bf16 v[122:125], v[168:171], v[176:179], v[122:125]
	v_mfma_f32_16x16x32_bf16 v[118:121], v[148:151], v[184:187], v[118:121]
	v_mfma_f32_16x16x32_bf16 v[114:117], v[168:171], v[184:187], v[114:117]
	v_mfma_f32_16x16x32_bf16 v[102:105], v[148:151], v[192:195], v[102:105]
	v_mfma_f32_16x16x32_bf16 v[98:101], v[168:171], v[192:195], v[98:101]
	v_mfma_f32_16x16x32_bf16 v[86:89], v[148:151], v[224:227], v[86:89]
	v_mfma_f32_16x16x32_bf16 v[82:85], v[168:171], v[224:227], v[82:85]
	v_mfma_f32_16x16x32_bf16 v[110:113], v[228:231], v[172:175], v[110:113]
	v_mfma_f32_16x16x32_bf16 v[106:109], v[236:239], v[172:175], v[106:109]
	v_mfma_f32_16x16x32_bf16 v[94:97], v[228:231], v[180:183], v[94:97]
	v_mfma_f32_16x16x32_bf16 v[90:93], v[236:239], v[180:183], v[90:93]
	v_mfma_f32_16x16x32_bf16 v[78:81], v[228:231], v[188:191], v[78:81]
	v_mfma_f32_16x16x32_bf16 v[74:77], v[236:239], v[188:191], v[74:77]
	v_mfma_f32_16x16x32_bf16 v[70:73], v[228:231], v[196:199], v[70:73]
	v_mfma_f32_16x16x32_bf16 v[66:69], v[236:239], v[196:199], v[66:69]
	v_mfma_f32_16x16x32_bf16 v[110:113], v[232:235], v[176:179], v[110:113]
	v_mfma_f32_16x16x32_bf16 v[106:109], v[240:243], v[176:179], v[106:109]
	v_mfma_f32_16x16x32_bf16 v[94:97], v[232:235], v[184:187], v[94:97]
	v_mfma_f32_16x16x32_bf16 v[90:93], v[240:243], v[184:187], v[90:93]
	v_mfma_f32_16x16x32_bf16 v[78:81], v[232:235], v[192:195], v[78:81]
	v_mfma_f32_16x16x32_bf16 v[74:77], v[240:243], v[192:195], v[74:77]
	v_mfma_f32_16x16x32_bf16 v[70:73], v[232:235], v[224:227], v[70:73]
	v_mfma_f32_16x16x32_bf16 v[66:69], v[240:243], v[224:227], v[66:69]
	s_barrier
	s_mov_b32 m0, s54
	s_add_u32 s78, s50, s94
	s_addc_u32 s79, s51, s95
	ds_read_b128 v[172:175], v143 offset:16384
	ds_read_b128 v[176:179], v143 offset:17408
	ds_read_b128 v[180:183], v143 offset:18432
	ds_read_b128 v[184:187], v143 offset:19456
	ds_read_b128 v[188:191], v143 offset:20480
	ds_read_b128 v[192:195], v143 offset:21504
	ds_read_b128 v[196:199], v143 offset:22528
	ds_read_b128 v[224:227], v143 offset:23552
	global_load_lds_dwordx4 v130, s[50:51]
	s_mov_b32 m0, s55
	s_add_u32 s76, s48, s94
	s_addc_u32 s77, s49, s95
	global_load_lds_dwordx4 v132, s[50:51]
	s_mov_b32 m0, s64
	s_nop 0
	global_load_lds_dwordx4 v0, s[48:49]
	s_add_i32 m0, s64, 0x2000
	s_add_u32 s64, s48, 0x80000
	s_addc_u32 s65, s49, 0
	global_load_lds_dwordx4 v134, s[48:49]
	s_add_i32 s39, s39, s53
	s_mov_b32 m0, s39
	s_nop 0
	global_load_lds_dwordx4 v0, s[64:65]
	s_add_i32 m0, s39, 0x2000
	s_nop 0
	global_load_lds_dwordx4 v134, s[64:65]
	s_waitcnt vmcnt(8) lgkmcnt(0)
	s_barrier
	v_mfma_f32_16x16x32_bf16 v[62:65], v[144:147], v[172:175], v[62:65]
	v_mfma_f32_16x16x32_bf16 v[58:61], v[152:155], v[172:175], v[58:61]
	v_mfma_f32_16x16x32_bf16 v[54:57], v[144:147], v[180:183], v[54:57]
	v_mfma_f32_16x16x32_bf16 v[50:53], v[152:155], v[180:183], v[50:53]
	v_mfma_f32_16x16x32_bf16 v[38:41], v[144:147], v[188:191], v[38:41]
	v_mfma_f32_16x16x32_bf16 v[34:37], v[152:155], v[188:191], v[34:37]
	v_mfma_f32_16x16x32_bf16 v[22:25], v[144:147], v[196:199], v[22:25]
	v_mfma_f32_16x16x32_bf16 v[18:21], v[152:155], v[196:199], v[18:21]
	v_mfma_f32_16x16x32_bf16 v[62:65], v[148:151], v[176:179], v[62:65]
	v_mfma_f32_16x16x32_bf16 v[58:61], v[168:171], v[176:179], v[58:61]
	v_mfma_f32_16x16x32_bf16 v[54:57], v[148:151], v[184:187], v[54:57]
	v_mfma_f32_16x16x32_bf16 v[50:53], v[168:171], v[184:187], v[50:53]
	v_mfma_f32_16x16x32_bf16 v[38:41], v[148:151], v[192:195], v[38:41]
	v_mfma_f32_16x16x32_bf16 v[34:37], v[168:171], v[192:195], v[34:37]
	v_mfma_f32_16x16x32_bf16 v[22:25], v[148:151], v[224:227], v[22:25]
	v_mfma_f32_16x16x32_bf16 v[18:21], v[168:171], v[224:227], v[18:21]
	v_mfma_f32_16x16x32_bf16 v[46:49], v[228:231], v[172:175], v[46:49]
	v_mfma_f32_16x16x32_bf16 v[42:45], v[236:239], v[172:175], v[42:45]
	v_mfma_f32_16x16x32_bf16 v[30:33], v[228:231], v[180:183], v[30:33]
	v_mfma_f32_16x16x32_bf16 v[26:29], v[236:239], v[180:183], v[26:29]
	v_mfma_f32_16x16x32_bf16 v[14:17], v[228:231], v[188:191], v[14:17]
	v_mfma_f32_16x16x32_bf16 v[10:13], v[236:239], v[188:191], v[10:13]
	v_mfma_f32_16x16x32_bf16 v[6:9], v[228:231], v[196:199], v[6:9]
	v_mfma_f32_16x16x32_bf16 v[2:5], v[236:239], v[196:199], v[2:5]
	v_mfma_f32_16x16x32_bf16 v[46:49], v[232:235], v[176:179], v[46:49]
	v_mfma_f32_16x16x32_bf16 v[42:45], v[240:243], v[176:179], v[42:45]
	v_mfma_f32_16x16x32_bf16 v[30:33], v[232:235], v[184:187], v[30:33]
	v_mfma_f32_16x16x32_bf16 v[26:29], v[240:243], v[184:187], v[26:29]
	v_mfma_f32_16x16x32_bf16 v[14:17], v[232:235], v[192:195], v[14:17]
	v_mfma_f32_16x16x32_bf16 v[10:13], v[240:243], v[192:195], v[10:13]
	v_mfma_f32_16x16x32_bf16 v[6:9], v[232:235], v[224:227], v[6:9]
	v_mfma_f32_16x16x32_bf16 v[2:5], v[240:243], v[224:227], v[2:5]
	s_barrier
	s_add_i32 s39, 0, 0x18000
	ds_read_b128 v[144:147], v141 offset:32768
	ds_read_b128 v[148:151], v141 offset:33792
	ds_read_b128 v[152:155], v141 offset:34816
	ds_read_b128 v[168:171], v141 offset:35840
	s_add_u32 s50, s50, 0x80000
	s_addc_u32 s51, s51, 0
	ds_read_b128 v[172:175], v143 offset:32768
	ds_read_b128 v[176:179], v143 offset:33792
	ds_read_b128 v[180:183], v143 offset:34816
	ds_read_b128 v[184:187], v143 offset:35840
	ds_read_b128 v[188:191], v143 offset:36864
	ds_read_b128 v[192:195], v143 offset:37888
	ds_read_b128 v[196:199], v143 offset:38912
	ds_read_b128 v[224:227], v143 offset:39936
	s_mov_b32 m0, s56
	s_nop 0
	global_load_lds_dwordx4 v130, s[50:51]
	s_mov_b32 m0, s57
	s_nop 0
	global_load_lds_dwordx4 v132, s[50:51]
	s_add_i32 s50, 0, 0x1c000
	s_add_i32 s39, s39, s53
	ds_read_b128 v[228:231], v141 offset:49152
	ds_read_b128 v[232:235], v141 offset:50176
	ds_read_b128 v[236:239], v141 offset:51200
	ds_read_b128 v[240:243], v141 offset:52224
	s_waitcnt vmcnt(8) lgkmcnt(0)
	s_nop 0
	s_barrier
	v_mfma_f32_16x16x32_bf16 v[126:129], v[144:147], v[172:175], v[126:129]
	v_mfma_f32_16x16x32_bf16 v[122:125], v[152:155], v[172:175], v[122:125]
	v_mfma_f32_16x16x32_bf16 v[118:121], v[144:147], v[180:183], v[118:121]
	v_mfma_f32_16x16x32_bf16 v[114:117], v[152:155], v[180:183], v[114:117]
	v_mfma_f32_16x16x32_bf16 v[102:105], v[144:147], v[188:191], v[102:105]
	v_mfma_f32_16x16x32_bf16 v[98:101], v[152:155], v[188:191], v[98:101]
	v_mfma_f32_16x16x32_bf16 v[86:89], v[144:147], v[196:199], v[86:89]
	v_mfma_f32_16x16x32_bf16 v[82:85], v[152:155], v[196:199], v[82:85]
	v_mfma_f32_16x16x32_bf16 v[126:129], v[148:151], v[176:179], v[126:129]
	v_mfma_f32_16x16x32_bf16 v[122:125], v[168:171], v[176:179], v[122:125]
	v_mfma_f32_16x16x32_bf16 v[118:121], v[148:151], v[184:187], v[118:121]
	v_mfma_f32_16x16x32_bf16 v[114:117], v[168:171], v[184:187], v[114:117]
	v_mfma_f32_16x16x32_bf16 v[102:105], v[148:151], v[192:195], v[102:105]
	v_mfma_f32_16x16x32_bf16 v[98:101], v[168:171], v[192:195], v[98:101]
	v_mfma_f32_16x16x32_bf16 v[86:89], v[148:151], v[224:227], v[86:89]
	v_mfma_f32_16x16x32_bf16 v[82:85], v[168:171], v[224:227], v[82:85]
	v_mfma_f32_16x16x32_bf16 v[110:113], v[228:231], v[172:175], v[110:113]
	v_mfma_f32_16x16x32_bf16 v[106:109], v[236:239], v[172:175], v[106:109]
	v_mfma_f32_16x16x32_bf16 v[94:97], v[228:231], v[180:183], v[94:97]
	v_mfma_f32_16x16x32_bf16 v[90:93], v[236:239], v[180:183], v[90:93]
	v_mfma_f32_16x16x32_bf16 v[78:81], v[228:231], v[188:191], v[78:81]
	v_mfma_f32_16x16x32_bf16 v[74:77], v[236:239], v[188:191], v[74:77]
	v_mfma_f32_16x16x32_bf16 v[70:73], v[228:231], v[196:199], v[70:73]
	v_mfma_f32_16x16x32_bf16 v[66:69], v[236:239], v[196:199], v[66:69]
	v_mfma_f32_16x16x32_bf16 v[110:113], v[232:235], v[176:179], v[110:113]
	v_mfma_f32_16x16x32_bf16 v[106:109], v[240:243], v[176:179], v[106:109]
	v_mfma_f32_16x16x32_bf16 v[94:97], v[232:235], v[184:187], v[94:97]
	v_mfma_f32_16x16x32_bf16 v[90:93], v[240:243], v[184:187], v[90:93]
	v_mfma_f32_16x16x32_bf16 v[78:81], v[232:235], v[192:195], v[78:81]
	v_mfma_f32_16x16x32_bf16 v[74:77], v[240:243], v[192:195], v[74:77]
	v_mfma_f32_16x16x32_bf16 v[70:73], v[232:235], v[224:227], v[70:73]
	v_mfma_f32_16x16x32_bf16 v[66:69], v[240:243], v[224:227], v[66:69]
	s_barrier
	s_mov_b32 m0, s59
	ds_read_b128 v[172:175], v143 offset:49152
	ds_read_b128 v[176:179], v143 offset:50176
	ds_read_b128 v[180:183], v143 offset:51200
	ds_read_b128 v[184:187], v143 offset:52224
	ds_read_b128 v[188:191], v143 offset:53248
	ds_read_b128 v[192:195], v143 offset:54272
	ds_read_b128 v[196:199], v143 offset:55296
	ds_read_b128 v[224:227], v143 offset:56320
	global_load_lds_dwordx4 v130, s[78:79]
	s_mov_b32 m0, s61
	s_nop 0
	global_load_lds_dwordx4 v132, s[78:79]
	s_mov_b32 m0, s39
	s_nop 0
	global_load_lds_dwordx4 v0, s[76:77]
	s_add_i32 m0, s39, 0x2000
	s_add_u32 s48, s48, 0x80080
	s_addc_u32 s49, s49, 0
	global_load_lds_dwordx4 v134, s[76:77]
	s_add_i32 s39, s50, s53
	s_mov_b32 m0, s39
	s_nop 0
	global_load_lds_dwordx4 v0, s[48:49]
	s_add_i32 m0, s39, 0x2000
	s_nop 0
	global_load_lds_dwordx4 v134, s[48:49]
	s_waitcnt vmcnt(8) lgkmcnt(0)
	s_nop 0
	s_barrier
	v_mfma_f32_16x16x32_bf16 v[62:65], v[144:147], v[172:175], v[62:65]
	v_mfma_f32_16x16x32_bf16 v[58:61], v[152:155], v[172:175], v[58:61]
	v_mfma_f32_16x16x32_bf16 v[54:57], v[144:147], v[180:183], v[54:57]
	v_mfma_f32_16x16x32_bf16 v[50:53], v[152:155], v[180:183], v[50:53]
	v_mfma_f32_16x16x32_bf16 v[38:41], v[144:147], v[188:191], v[38:41]
	v_mfma_f32_16x16x32_bf16 v[34:37], v[152:155], v[188:191], v[34:37]
	v_mfma_f32_16x16x32_bf16 v[22:25], v[144:147], v[196:199], v[22:25]
	v_mfma_f32_16x16x32_bf16 v[18:21], v[152:155], v[196:199], v[18:21]
	v_mfma_f32_16x16x32_bf16 v[62:65], v[148:151], v[176:179], v[62:65]
	v_mfma_f32_16x16x32_bf16 v[58:61], v[168:171], v[176:179], v[58:61]
	v_mfma_f32_16x16x32_bf16 v[54:57], v[148:151], v[184:187], v[54:57]
	v_mfma_f32_16x16x32_bf16 v[50:53], v[168:171], v[184:187], v[50:53]
	v_mfma_f32_16x16x32_bf16 v[38:41], v[148:151], v[192:195], v[38:41]
	v_mfma_f32_16x16x32_bf16 v[34:37], v[168:171], v[192:195], v[34:37]
	v_mfma_f32_16x16x32_bf16 v[22:25], v[148:151], v[224:227], v[22:25]
	v_mfma_f32_16x16x32_bf16 v[18:21], v[168:171], v[224:227], v[18:21]
	v_mfma_f32_16x16x32_bf16 v[46:49], v[228:231], v[172:175], v[46:49]
	v_mfma_f32_16x16x32_bf16 v[42:45], v[236:239], v[172:175], v[42:45]
	v_mfma_f32_16x16x32_bf16 v[30:33], v[228:231], v[180:183], v[30:33]
	v_mfma_f32_16x16x32_bf16 v[26:29], v[236:239], v[180:183], v[26:29]
	v_mfma_f32_16x16x32_bf16 v[14:17], v[228:231], v[188:191], v[14:17]
	v_mfma_f32_16x16x32_bf16 v[10:13], v[236:239], v[188:191], v[10:13]
	v_mfma_f32_16x16x32_bf16 v[6:9], v[228:231], v[196:199], v[6:9]
	v_mfma_f32_16x16x32_bf16 v[2:5], v[236:239], v[196:199], v[2:5]
	v_mfma_f32_16x16x32_bf16 v[46:49], v[232:235], v[176:179], v[46:49]
	v_mfma_f32_16x16x32_bf16 v[42:45], v[240:243], v[176:179], v[42:45]
	v_mfma_f32_16x16x32_bf16 v[30:33], v[232:235], v[184:187], v[30:33]
	v_mfma_f32_16x16x32_bf16 v[26:29], v[240:243], v[184:187], v[26:29]
	v_mfma_f32_16x16x32_bf16 v[14:17], v[232:235], v[192:195], v[14:17]
	v_mfma_f32_16x16x32_bf16 v[10:13], v[240:243], v[192:195], v[10:13]
	v_mfma_f32_16x16x32_bf16 v[6:9], v[232:235], v[224:227], v[6:9]
	v_mfma_f32_16x16x32_bf16 v[2:5], v[240:243], v[224:227], v[2:5]
	s_barrier
	s_add_i32 s13, s13, 2
	s_add_u32 s46, s46, 0x100
	s_addc_u32 s47, s47, 0
	s_add_u32 s1, s1, 0x100
	s_addc_u32 s12, s12, 0
	s_cmp_gt_u32 s13, 29
	s_cbranch_scc0 .LBB0_788
	s_cmp_lg_u32 s62, 0
	s_cbranch_scc0 .LBB0_791
	s_lshl_b32 s1, s60, 8
	s_mov_b64 s[12:13], 0
	s_branch .LBB0_792
